# v38 + next-tile prefetch: dummy loads of the next tile's first A/B lines issued after the peeled K-step barrier
# speedup vs baseline: 1.0054x; 1.0054x over previous
; template <int MODE, bool SWAP, int MT>
; DI void gemm_tile(const int wv_, const Params& p, const u16* __restrict__ A, const u16* __restrict__ Bt, int brow, int bcol, char* smem, const float* gnext) {
;     ...
;   for (int t = 0; t < 32; ++t) {
;     asm volatile("s_waitcnt vmcnt(0)" ::: "memory");
;     __syncthreads();
;     if (t + 1 < 32) stage(t + 1, (t + 1) & 1);
;     const char* sA = smem + (t & 1) * 24576; const char* sB = sA + 16384;
;     bf16x8 Af[MT], Bf[4];
; #pragma unroll
;     for (int n = 0; n < 4; ++n) Bf[n] = *(const bf16x8*)(sB + (wc * 64 + n * 16 + fr) * 64 + fq * 16);
;     constexpr int MH = MT >= 2 ? MT / 2 : 1;
; #pragma unroll
;     for (int m = 0; m < MH; ++m) Af[m] = *(const bf16x8*)(sA + (wr * (16 * MT) + m * 16 + fr) * 64 + fq * 16);
;     __builtin_amdgcn_sched_barrier(0);
; #pragma unroll
;     for (int m = MH; m < MT; ++m) Af[m] = *(const bf16x8*)(sA + (wr * (16 * MT) + m * 16 + fr) * 64 + fq * 16);
; #pragma unroll
;     for (int m = 0; m < MH; ++m)
; #pragma unroll
;       for (int n = 0; n < 4; ++n)
;         acc[m][n] = SWAP ? __builtin_amdgcn_mfma_f32_16x16x32_bf16(Bf[n], Af[m], acc[m][n], 0, 0, 0)
;                          : __builtin_amdgcn_mfma_f32_16x16x32_bf16(Af[m], Bf[n], acc[m][n], 0, 0, 0);
;     __builtin_amdgcn_sched_barrier(0);
; #pragma unroll
;     for (int m = MH; m < MT; ++m)
; #pragma unroll
;       for (int n = 0; n < 4; ++n)
;         acc[m][n] = SWAP ? __builtin_amdgcn_mfma_f32_16x16x32_bf16(Bf[n], Af[m], acc[m][n], 0, 0, 0)
;                          : __builtin_amdgcn_mfma_f32_16x16x32_bf16(Af[m], Bf[n], acc[m][n], 0, 0, 0);
;   }
; template <int MODE>
; DI void phase_gemm(const int wv_, const Params& p, const u16* A, const u16* Bt, int NT, char* smem, const float* gnext) {
;     ...
;   for (int tile = bid_; tile < nfull; tile += nblk_) {
;     int tm = tile / NT, tn = tile - tm * NT;
;     if (MODE == 1 && tn >= 20 && tn < 24) gemm_tile<1, false, 4>(wv_, p, A, Bt, tm * 256, tn * 128, smem, gnext);
;     else gemm_tile<MODE, true, 4>(wv_, p, A, Bt, tm * 256, tn * 128, smem, gnext);
.LBB0_86:
	s_add_i32 s1, s0, 1
	s_bitcmp1_b32 s1, 0
	s_cselect_b32 s20, 0x6000, 0
	v_add_u32_e32 v2, s20, v76
	v_add_u32_e32 v80, 0x2000, v2
	v_readfirstlane_b32 s20, v2
	s_mov_b32 m0, s20
	v_readfirstlane_b32 s20, v80
	v_add_u32_e32 v2, 0x4000, v2
	s_waitcnt vmcnt(0)
	s_waitcnt vmcnt(0) lgkmcnt(0)
	s_barrier
	global_load_lds_dwordx4 v[0:1], off
	s_mov_b32 m0, s20
	v_readfirstlane_b32 s20, v2
	global_load_lds_dwordx4 v[68:69], off
	s_mov_b32 m0, s20
	s_bitcmp1_b32 s0, 0
	global_load_lds_dwordx4 v[70:71], off
	s_cselect_b32 s0, 0x6000, 0
	v_or_b32_e32 v2, s0, v77
	v_add_u32_e32 v92, v2, v78
	ds_read_b128 v[80:83], v92 offset:16384
	ds_read_b128 v[84:87], v92 offset:17408
	ds_read_b128 v[88:91], v92 offset:18432
	ds_read_b128 v[92:95], v92 offset:19456
	v_add_u32_e32 v2, v2, v79
	ds_read_b128 v[96:99], v2
	ds_read_b128 v[100:103], v2 offset:1024
	s_waitcnt lgkmcnt(0)
	v_mfma_f32_16x16x32_bf16 v[64:67], v[80:83], v[96:99], v[64:67]
	v_mfma_f32_16x16x32_bf16 v[60:63], v[84:87], v[96:99], v[60:63]
	v_mfma_f32_16x16x32_bf16 v[56:59], v[88:91], v[96:99], v[56:59]
	v_mfma_f32_16x16x32_bf16 v[52:55], v[92:95], v[96:99], v[52:55]
	ds_read_b128 v[96:99], v2 offset:2048
	ds_read_b128 v[104:107], v2 offset:3072
	v_mfma_f32_16x16x32_bf16 v[48:51], v[80:83], v[100:103], v[48:51]
	v_mfma_f32_16x16x32_bf16 v[40:43], v[84:87], v[100:103], v[40:43]
	v_mfma_f32_16x16x32_bf16 v[36:39], v[88:91], v[100:103], v[36:39]
	v_mfma_f32_16x16x32_bf16 v[44:47], v[92:95], v[100:103], v[44:47]
	s_waitcnt lgkmcnt(0)
	v_mfma_f32_16x16x32_bf16 v[32:35], v[80:83], v[96:99], v[32:35]
	v_lshl_add_u64 v[0:1], v[0:1], 0, 64
	v_lshl_add_u64 v[68:69], v[68:69], 0, 64
	v_lshl_add_u64 v[70:71], v[70:71], 0, 64
	v_mfma_f32_16x16x32_bf16 v[28:31], v[84:87], v[96:99], v[28:31]
	s_cmp_lg_u32 s1, 31
	s_mov_b32 s0, s1
	v_mfma_f32_16x16x32_bf16 v[24:27], v[88:91], v[96:99], v[24:27]
	v_mfma_f32_16x16x32_bf16 v[20:23], v[92:95], v[96:99], v[20:23]
	v_mfma_f32_16x16x32_bf16 v[16:19], v[80:83], v[104:107], v[16:19]
	v_mfma_f32_16x16x32_bf16 v[12:15], v[84:87], v[104:107], v[12:15]
	v_mfma_f32_16x16x32_bf16 v[8:11], v[88:91], v[104:107], v[8:11]
	v_mfma_f32_16x16x32_bf16 v[4:7], v[92:95], v[104:107], v[4:7]
	s_cbranch_scc1 .LBB0_86
	s_add_i32 s98, s14, s7
	s_cmp_lt_i32 s98, s8
	s_cselect_b32 s98, s98, s14
	s_lshr_b32 s99, s98, 2
	s_mul_i32 s99, s99, 9363
	s_lshr_b32 s99, s99, 16
	s_mul_i32 s100, s99, 28
	s_sub_i32 s100, s98, s100
	s_lshl_b32 s99, s99, 8
	s_sub_i32 s98, s99, s18
	s_add_i32 s98, s98, -1
	s_ashr_i32 s99, s98, 31
	s_lshl_b64 s[98:99], s[98:99], 11
	s_lshl_b32 s100, s100, 7
	s_sub_i32 s100, s100, s15
	s_add_i32 s100, s100, -1
	s_ashr_i32 s101, s100, 31
	s_lshl_b64 s[100:101], s[100:101], 11
	v_lshl_add_u64 v[112:113], v[0:1], 0, s[98:99]
	v_lshl_add_u64 v[114:115], v[68:69], 0, s[98:99]
	v_lshl_add_u64 v[116:117], v[70:71], 0, s[100:101]
	v_add_u32_e32 v0, v77, v79
	v_add_u32_e32 v1, v77, v78
	s_waitcnt vmcnt(0)
	s_waitcnt vmcnt(0)
	s_barrier
	global_load_dword v108, v[112:113], off
	global_load_dword v109, v[114:115], off
	global_load_dword v110, v[116:117], off
	ds_read_b128 v[68:71], v0 offset:25600
	ds_read_b128 v[80:83], v0 offset:24576
	ds_read_b128 v[76:79], v1 offset:44032
	ds_read_b128 v[84:87], v1 offset:43008
	ds_read_b128 v[88:91], v1 offset:41984
	ds_read_b128 v[92:95], v1 offset:40960
	s_waitcnt lgkmcnt(0)
	v_mfma_f32_16x16x32_bf16 v[64:67], v[92:95], v[80:83], v[64:67]
	v_mfma_f32_16x16x32_bf16 v[60:63], v[88:91], v[80:83], v[60:63]
	v_mfma_f32_16x16x32_bf16 v[56:59], v[84:87], v[80:83], v[56:59]
	v_mfma_f32_16x16x32_bf16 v[52:55], v[76:79], v[80:83], v[52:55]
	ds_read_b128 v[80:83], v0 offset:26624
	ds_read_b128 v[96:99], v0 offset:27648
	v_mfma_f32_16x16x32_bf16 v[48:51], v[92:95], v[68:71], v[48:51]
	v_mfma_f32_16x16x32_bf16 v[40:43], v[88:91], v[68:71], v[40:43]
	v_mfma_f32_16x16x32_bf16 v[36:39], v[84:87], v[68:71], v[36:39]
	v_mfma_f32_16x16x32_bf16 v[44:47], v[76:79], v[68:71], v[44:47]
	v_or_b32_e32 v0, s18, v74
	v_lshl_add_u32 v68, v73, 6, v0
	v_lshlrev_b32_e32 v0, 6, v72
	v_lshlrev_b32_e32 v1, 2, v75
	v_ashrrev_i32_e32 v69, 31, v68
	v_or3_b32 v70, v0, v1, s15
	v_lshlrev_b64 v[0:1], 6, v[68:69]
	v_lshl_add_u64 v[0:1], s[90:91], 0, v[0:1]
	s_waitcnt lgkmcnt(1)
	v_mfma_f32_16x16x32_bf16 v[32:35], v[92:95], v[80:83], v[32:35]
	s_waitcnt lgkmcnt(0)
	s_barrier
; DI unsigned pack2(float a, float b) { f32x2_t v = {a, b}; return __builtin_bit_cast(unsigned, __builtin_convertvector(v, bf16x2_t)); }
; template <int MODE, bool SWAP, int MT>
; DI void gemm_tile(const int wv_, const Params& p, const u16* __restrict__ A, const u16* __restrict__ Bt, int brow, int bcol, char* smem, const float* gnext) {
;     ...
;       } else {
;         const float rs = rowscale(p.ss, R);
; #pragma unroll
;         for (int n = 0; n < 4; ++n) { acc[m][n][0] *= rs; acc[m][n][1] *= rs; acc[m][n][2] *= rs; acc[m][n][3] *= rs; }
;         if (MODE == 0 && bcol >= 512 && bcol < 1536) {
;           int b = R / P, pos = R - b * P;
;           u16* dstb = (bcol < 1024 ? p.kc : p.vc);
; #pragma unroll
;           for (int n = 0; n < 4; ++n) {
;             int cc = (bcol & 511) + wc * 64 + n * 16 + fq * 4;
;             uint2 o; o.x = pack2(acc[m][n][0], acc[m][n][1]); o.y = pack2(acc[m][n][2], acc[m][n][3]);
;             *(uint2*)(dstb + ((size_t)((b * 8 + (cc >> 6)) * P + pos)) * 64 + (cc & 63)) = o;
;           }
;         } else {
;           const int LD = MODE == 0 ? LD_AB : LD_CD;
;           u16* pr = p.proj + (size_t)R * LD;
; #pragma unroll
;           for (int n = 0; n < 4; ++n) {
;             int col = bcol + wc * 64 + n * 16 + fq * 4;
;             if (MODE == 1 || col < 4184) {
;               uint2 o; o.x = pack2(acc[m][n][0], acc[m][n][1]); o.y = pack2(acc[m][n][2], acc[m][n][3]);
;               int pcol = (MODE == 0 && col >= 1536) ? col - 1024 : col;
;               *(uint2*)(pr + pcol) = o;
;               if (MODE == 0 && col >= 2560 && col < 2624) *(uint2*)(p.ikc + (size_t)R * 64 + (col - 2560)) = o;
;             }
;           }
	v_mfma_f32_16x16x32_bf16 v[28:31], v[88:91], v[80:83], v[28:31]
	v_mov_b32_e32 v69, 0x358637bd
	v_ashrrev_i32_e32 v71, 31, v70
	v_mfma_f32_16x16x32_bf16 v[24:27], v[84:87], v[80:83], v[24:27]
	v_mfma_f32_16x16x32_bf16 v[20:23], v[76:79], v[80:83], v[20:23]
	v_mfma_f32_16x16x32_bf16 v[8:11], v[84:87], v[96:99], v[8:11]
	v_mfma_f32_16x16x32_bf16 v[4:7], v[76:79], v[96:99], v[4:7]
	global_load_dwordx4 v[72:75], v[0:1], off offset:32
	global_load_dwordx4 v[76:79], v[0:1], off offset:16
	global_load_dwordx4 v[80:83], v[0:1], off
	global_load_dwordx4 v[84:87], v[0:1], off offset:48
	s_waitcnt vmcnt(3)
	v_mov_b32_e32 v2, v73
	v_mfma_f32_16x16x32_bf16 v[12:15], v[88:91], v[96:99], v[12:15]
	s_waitcnt vmcnt(1)
	v_mov_b32_e32 v0, v81
	v_mov_b32_e32 v1, v82
	v_mov_b32_e32 v88, v77
	v_mov_b32_e32 v89, v78
	v_mov_b32_e32 v81, v83
	v_mov_b32_e32 v77, v79
	v_pk_add_f32 v[0:1], v[0:1], v[80:81]
	v_pk_add_f32 v[76:77], v[88:89], v[76:77]
	v_pk_add_f32 v[72:73], v[72:73], v[2:3]
	v_mov_b32_e32 v2, v75
	v_pk_add_f32 v[0:1], v[0:1], v[0:1] op_sel:[0,1] op_sel_hi:[1,0]
	v_pk_add_f32 v[76:77], v[76:77], v[76:77] op_sel:[0,1] op_sel_hi:[1,0]
	v_pk_add_f32 v[74:75], v[74:75], v[2:3]
	s_waitcnt vmcnt(0)
	v_mov_b32_e32 v1, v84
	v_mov_b32_e32 v77, v85
	v_mov_b32_e32 v73, v86
	v_mov_b32_e32 v75, v87
	v_pk_add_f32 v[0:1], v[0:1], v[76:77]
	v_pk_add_f32 v[72:73], v[72:73], v[74:75]
	v_mfma_f32_16x16x32_bf16 v[16:19], v[92:95], v[96:99], v[16:19]
	v_add_f32_e64 v0, v0, v72
	v_add_f32_e64 v1, v1, v73
	v_add_f32_e32 v0, v0, v1
	v_fmamk_f32 v0, v0, 0x3a800000, v69
	v_cmp_gt_f32_e32 vcc, s96, v0
	v_mul_f32_e32 v1, 0x4b800000, v0
	s_nop 0
	v_cndmask_b32_e32 v0, v0, v1, vcc
	v_rsq_f32_e32 v0, v0
	s_nop 0
	v_mul_f32_e32 v1, 0x45800000, v0
	v_cndmask_b32_e32 v0, v0, v1, vcc
	v_pk_mul_f32 v[72:73], v[64:65], v[0:1] op_sel_hi:[1,0]
	v_pk_mul_f32 v[66:67], v[66:67], v[0:1] op_sel_hi:[1,0]
	v_pk_mul_f32 v[64:65], v[60:61], v[0:1] op_sel_hi:[1,0]
	v_pk_mul_f32 v[62:63], v[62:63], v[0:1] op_sel_hi:[1,0]
	v_pk_mul_f32 v[60:61], v[56:57], v[0:1] op_sel_hi:[1,0]
	v_pk_mul_f32 v[58:59], v[58:59], v[0:1] op_sel_hi:[1,0]
	v_pk_mul_f32 v[56:57], v[52:53], v[0:1] op_sel_hi:[1,0]
	v_pk_mul_f32 v[54:55], v[54:55], v[0:1] op_sel_hi:[1,0]
	v_mov_b64_e32 v[0:1], s[68:69]
	v_mad_i64_i32 v[74:75], s[0:1], v68, s34, v[0:1]
	v_lshlrev_b64 v[52:53], 1, v[70:71]
	v_cvt_pk_bf16_f32 v56, v56, v57
	v_cvt_pk_bf16_f32 v57, v54, v55
	v_or_b32_e32 v54, 16, v68
	v_cvt_pk_bf16_f32 v72, v72, v73
	v_cvt_pk_bf16_f32 v73, v66, v67
	v_lshl_add_u64 v[66:67], v[74:75], 0, v[52:53]
	v_ashrrev_i32_e32 v55, 31, v54
	v_cvt_pk_bf16_f32 v64, v64, v65
	v_cvt_pk_bf16_f32 v65, v62, v63
	v_cvt_pk_bf16_f32 v60, v60, v61
	v_cvt_pk_bf16_f32 v61, v58, v59
	global_store_dwordx2 v[66:67], v[56:57], off offset:96
	v_lshlrev_b64 v[56:57], 6, v[54:55]
	global_store_dwordx2 v[66:67], v[72:73], off
	global_store_dwordx2 v[66:67], v[64:65], off offset:32
	global_store_dwordx2 v[66:67], v[60:61], off offset:64
	v_lshl_add_u64 v[70:71], s[90:91], 0, v[56:57]
	global_load_dwordx4 v[56:59], v[70:71], off offset:32
	global_load_dwordx4 v[60:63], v[70:71], off offset:16
	global_load_dwordx4 v[64:67], v[70:71], off
	s_nop 0
	global_load_dwordx4 v[70:73], v[70:71], off offset:48
	s_waitcnt vmcnt(3)
	v_mov_b32_e32 v2, v57
	s_waitcnt vmcnt(2)
	v_mov_b32_e32 v76, v61
	s_waitcnt vmcnt(1)
	v_mov_b32_e32 v74, v65
	v_mov_b32_e32 v75, v66
	v_mov_b32_e32 v77, v62
	v_mov_b32_e32 v65, v67
	v_mov_b32_e32 v61, v63
	v_pk_add_f32 v[64:65], v[74:75], v[64:65]
	v_pk_add_f32 v[60:61], v[76:77], v[60:61]
	v_pk_add_f32 v[56:57], v[56:57], v[2:3]
	v_mov_b32_e32 v2, v59
	v_pk_add_f32 v[64:65], v[64:65], v[64:65] op_sel:[0,1] op_sel_hi:[1,0]
	v_pk_add_f32 v[60:61], v[60:61], v[60:61] op_sel:[0,1] op_sel_hi:[1,0]
	v_pk_add_f32 v[58:59], v[58:59], v[2:3]
	s_waitcnt vmcnt(0)
	v_mov_b32_e32 v65, v70
	v_mov_b32_e32 v61, v71
	v_mov_b32_e32 v57, v72
	v_mov_b32_e32 v59, v73
	v_pk_add_f32 v[60:61], v[64:65], v[60:61]
	v_pk_add_f32 v[56:57], v[56:57], v[58:59]
	s_nop 0
	v_pk_add_f32 v[56:57], v[60:61], v[56:57]
	s_nop 0
	v_add_f32_e32 v2, v56, v57
	v_fmamk_f32 v2, v2, 0x3a800000, v69
	v_cmp_gt_f32_e32 vcc, s96, v2
	v_mul_f32_e32 v55, 0x4b800000, v2
	s_nop 0
	v_cndmask_b32_e32 v2, v2, v55, vcc
	v_rsq_f32_e32 v2, v2
	s_nop 0
	v_mul_f32_e32 v55, 0x45800000, v2
	v_cndmask_b32_e32 v2, v2, v55, vcc
	v_pk_mul_f32 v[48:49], v[48:49], v[2:3] op_sel_hi:[1,0]
	v_pk_mul_f32 v[50:51], v[50:51], v[2:3] op_sel_hi:[1,0]
	v_pk_mul_f32 v[36:37], v[36:37], v[2:3] op_sel_hi:[1,0]
	v_pk_mul_f32 v[38:39], v[38:39], v[2:3] op_sel_hi:[1,0]
	v_mad_i64_i32 v[54:55], s[0:1], v54, s34, v[0:1]
	v_pk_mul_f32 v[44:45], v[44:45], v[2:3] op_sel_hi:[1,0]
	v_cvt_pk_bf16_f32 v48, v48, v49
	v_cvt_pk_bf16_f32 v49, v50, v51
	v_lshl_add_u64 v[50:51], v[54:55], 0, v[52:53]
	v_cvt_pk_bf16_f32 v36, v36, v37
	v_cvt_pk_bf16_f32 v37, v38, v39
	v_pk_mul_f32 v[46:47], v[46:47], v[2:3] op_sel_hi:[1,0]
	global_store_dwordx2 v[50:51], v[36:37], off offset:64
	v_cvt_pk_bf16_f32 v36, v44, v45
	v_or_b32_e32 v44, 32, v68
	v_pk_mul_f32 v[40:41], v[40:41], v[2:3] op_sel_hi:[1,0]
	v_pk_mul_f32 v[42:43], v[42:43], v[2:3] op_sel_hi:[1,0]
	v_cvt_pk_bf16_f32 v37, v46, v47
	v_ashrrev_i32_e32 v45, 31, v44
	v_cvt_pk_bf16_f32 v40, v40, v41
	v_cvt_pk_bf16_f32 v41, v42, v43
	global_store_dwordx2 v[50:51], v[36:37], off offset:96
	v_lshlrev_b64 v[36:37], 6, v[44:45]
	global_store_dwordx2 v[50:51], v[48:49], off
	global_store_dwordx2 v[50:51], v[40:41], off offset:32
	v_lshl_add_u64 v[50:51], s[90:91], 0, v[36:37]
	global_load_dwordx4 v[36:39], v[50:51], off offset:32
	global_load_dwordx4 v[40:43], v[50:51], off offset:16
	global_load_dwordx4 v[46:49], v[50:51], off
	global_load_dwordx4 v[54:57], v[50:51], off offset:48
	s_waitcnt vmcnt(3)
; DI unsigned pack2(float a, float b) { f32x2_t v = {a, b}; return __builtin_bit_cast(unsigned, __builtin_convertvector(v, bf16x2_t)); }
; template <int MODE, bool SWAP, int MT>
; DI void gemm_tile(const int wv_, const Params& p, const u16* __restrict__ A, const u16* __restrict__ Bt, int brow, int bcol, char* smem, const float* gnext) {
;     ...
;       } else {
;         const float rs = rowscale(p.ss, R);
; #pragma unroll
;         for (int n = 0; n < 4; ++n) { acc[m][n][0] *= rs; acc[m][n][1] *= rs; acc[m][n][2] *= rs; acc[m][n][3] *= rs; }
;         if (MODE == 0 && bcol >= 512 && bcol < 1536) {
;           int b = R / P, pos = R - b * P;
;           u16* dstb = (bcol < 1024 ? p.kc : p.vc);
; #pragma unroll
;           for (int n = 0; n < 4; ++n) {
;             int cc = (bcol & 511) + wc * 64 + n * 16 + fq * 4;
;             uint2 o; o.x = pack2(acc[m][n][0], acc[m][n][1]); o.y = pack2(acc[m][n][2], acc[m][n][3]);
;             *(uint2*)(dstb + ((size_t)((b * 8 + (cc >> 6)) * P + pos)) * 64 + (cc & 63)) = o;
;           }
;         } else {
;           const int LD = MODE == 0 ? LD_AB : LD_CD;
;           u16* pr = p.proj + (size_t)R * LD;
; #pragma unroll
;           for (int n = 0; n < 4; ++n) {
;             int col = bcol + wc * 64 + n * 16 + fq * 4;
;             if (MODE == 1 || col < 4184) {
;               uint2 o; o.x = pack2(acc[m][n][0], acc[m][n][1]); o.y = pack2(acc[m][n][2], acc[m][n][3]);
;               int pcol = (MODE == 0 && col >= 1536) ? col - 1024 : col;
;               *(uint2*)(pr + pcol) = o;
;               if (MODE == 0 && col >= 2560 && col < 2624) *(uint2*)(p.ikc + (size_t)R * 64 + (col - 2560)) = o;
;             }
;           }
	v_mov_b32_e32 v2, v37
	s_waitcnt vmcnt(2)
	v_mov_b32_e32 v58, v41
	s_waitcnt vmcnt(1)
	v_mov_b32_e32 v50, v47
	v_mov_b32_e32 v51, v48
	v_mov_b32_e32 v59, v42
	v_mov_b32_e32 v47, v49
	v_mov_b32_e32 v41, v43
	v_pk_add_f32 v[46:47], v[50:51], v[46:47]
	v_pk_add_f32 v[40:41], v[58:59], v[40:41]
	v_pk_add_f32 v[36:37], v[36:37], v[2:3]
	v_mov_b32_e32 v2, v39
	v_pk_add_f32 v[46:47], v[46:47], v[46:47] op_sel:[0,1] op_sel_hi:[1,0]
	v_pk_add_f32 v[40:41], v[40:41], v[40:41] op_sel:[0,1] op_sel_hi:[1,0]
	v_pk_add_f32 v[38:39], v[38:39], v[2:3]
	s_waitcnt vmcnt(0)
	v_mov_b32_e32 v47, v54
	v_mov_b32_e32 v41, v55
	v_mov_b32_e32 v37, v56
	v_mov_b32_e32 v39, v57
	v_pk_add_f32 v[40:41], v[46:47], v[40:41]
	v_pk_add_f32 v[36:37], v[36:37], v[38:39]
	s_nop 0
	v_pk_add_f32 v[36:37], v[40:41], v[36:37]
	s_nop 0
	v_add_f32_e32 v2, v36, v37
	v_fmamk_f32 v2, v2, 0x3a800000, v69
	v_cmp_gt_f32_e32 vcc, s96, v2
	v_mul_f32_e32 v36, 0x4b800000, v2
	s_nop 0
	v_cndmask_b32_e32 v2, v2, v36, vcc
	v_rsq_f32_e32 v2, v2
	s_nop 0
	v_mul_f32_e32 v36, 0x45800000, v2
	v_cndmask_b32_e32 v2, v2, v36, vcc
	v_pk_mul_f32 v[32:33], v[32:33], v[2:3] op_sel_hi:[1,0]
	v_pk_mul_f32 v[34:35], v[34:35], v[2:3] op_sel_hi:[1,0]
	v_pk_mul_f32 v[28:29], v[28:29], v[2:3] op_sel_hi:[1,0]
	v_pk_mul_f32 v[30:31], v[30:31], v[2:3] op_sel_hi:[1,0]
	v_mad_i64_i32 v[36:37], s[0:1], v44, s34, v[0:1]
	v_cvt_pk_bf16_f32 v32, v32, v33
	v_cvt_pk_bf16_f32 v33, v34, v35
	v_lshl_add_u64 v[34:35], v[36:37], 0, v[52:53]
	v_cvt_pk_bf16_f32 v28, v28, v29
	v_cvt_pk_bf16_f32 v29, v30, v31
	v_pk_mul_f32 v[20:21], v[20:21], v[2:3] op_sel_hi:[1,0]
	v_pk_mul_f32 v[22:23], v[22:23], v[2:3] op_sel_hi:[1,0]
	global_store_dwordx2 v[34:35], v[28:29], off offset:32
	v_or_b32_e32 v28, 48, v68
	v_pk_mul_f32 v[24:25], v[24:25], v[2:3] op_sel_hi:[1,0]
	v_pk_mul_f32 v[26:27], v[26:27], v[2:3] op_sel_hi:[1,0]
	v_cvt_pk_bf16_f32 v20, v20, v21
	v_cvt_pk_bf16_f32 v21, v22, v23
	v_ashrrev_i32_e32 v29, 31, v28
	v_cvt_pk_bf16_f32 v24, v24, v25
	v_cvt_pk_bf16_f32 v25, v26, v27
	global_store_dwordx2 v[34:35], v[20:21], off offset:96
	v_lshlrev_b64 v[20:21], 6, v[28:29]
	global_store_dwordx2 v[34:35], v[32:33], off
	global_store_dwordx2 v[34:35], v[24:25], off offset:64
	v_lshl_add_u64 v[34:35], s[90:91], 0, v[20:21]
	global_load_dwordx4 v[20:23], v[34:35], off offset:32
	global_load_dwordx4 v[24:27], v[34:35], off offset:16
	global_load_dwordx4 v[30:33], v[34:35], off
	s_nop 0
	global_load_dwordx4 v[34:37], v[34:35], off offset:48
	v_mad_i64_i32 v[0:1], s[0:1], v28, s34, v[0:1]
	v_lshl_add_u64 v[0:1], v[0:1], 0, v[52:53]
	s_mov_b64 s[0:1], 0x60
	s_waitcnt vmcnt(3)
	v_mov_b32_e32 v2, v21
	s_waitcnt vmcnt(2)
	v_mov_b32_e32 v40, v25
	s_waitcnt vmcnt(1)
	v_mov_b32_e32 v38, v31
	v_mov_b32_e32 v39, v32
	v_mov_b32_e32 v41, v26
	v_mov_b32_e32 v31, v33
	v_mov_b32_e32 v25, v27
	v_pk_add_f32 v[30:31], v[38:39], v[30:31]
	v_pk_add_f32 v[24:25], v[40:41], v[24:25]
	v_pk_add_f32 v[20:21], v[20:21], v[2:3]
	v_mov_b32_e32 v2, v23
	v_pk_add_f32 v[30:31], v[30:31], v[30:31] op_sel:[0,1] op_sel_hi:[1,0]
	v_pk_add_f32 v[24:25], v[24:25], v[24:25] op_sel:[0,1] op_sel_hi:[1,0]
	v_pk_add_f32 v[22:23], v[22:23], v[2:3]
	s_waitcnt vmcnt(0)
	v_mov_b32_e32 v31, v34
	v_mov_b32_e32 v25, v35
	v_mov_b32_e32 v21, v36
	v_mov_b32_e32 v23, v37
	v_pk_add_f32 v[24:25], v[30:31], v[24:25]
	v_pk_add_f32 v[20:21], v[20:21], v[22:23]
	s_nop 0
	v_pk_add_f32 v[20:21], v[24:25], v[20:21]
	s_nop 0
	v_add_f32_e32 v2, v20, v21
	v_fmamk_f32 v2, v2, 0x3a800000, v69
	v_cmp_gt_f32_e32 vcc, s96, v2
	v_mul_f32_e32 v20, 0x4b800000, v2
	s_nop 0
	v_cndmask_b32_e32 v2, v2, v20, vcc
	v_rsq_f32_e32 v2, v2
	s_nop 0
	v_mul_f32_e32 v20, 0x45800000, v2
	v_cndmask_b32_e32 v2, v2, v20, vcc
	v_pk_mul_f32 v[16:17], v[16:17], v[2:3] op_sel_hi:[1,0]
	v_pk_mul_f32 v[18:19], v[18:19], v[2:3] op_sel_hi:[1,0]
	v_pk_mul_f32 v[12:13], v[12:13], v[2:3] op_sel_hi:[1,0]
	v_pk_mul_f32 v[14:15], v[14:15], v[2:3] op_sel_hi:[1,0]
	v_pk_mul_f32 v[20:21], v[4:5], v[2:3] op_sel_hi:[1,0]
	v_pk_mul_f32 v[4:5], v[6:7], v[2:3] op_sel_hi:[1,0]
	v_cvt_pk_bf16_f32 v6, v16, v17
	v_cvt_pk_bf16_f32 v7, v18, v19
	v_pk_mul_f32 v[8:9], v[8:9], v[2:3] op_sel_hi:[1,0]
	v_pk_mul_f32 v[10:11], v[10:11], v[2:3] op_sel_hi:[1,0]
	global_store_dwordx2 v[0:1], v[6:7], off
	v_cvt_pk_bf16_f32 v6, v12, v13
	v_cvt_pk_bf16_f32 v7, v14, v15
	global_store_dwordx2 v[0:1], v[6:7], off offset:32
	v_cvt_pk_bf16_f32 v6, v8, v9
	v_cvt_pk_bf16_f32 v7, v10, v11
	global_store_dwordx2 v[0:1], v[6:7], off offset:64
	v_cvt_pk_bf16_f32 v2, v20, v21
	v_lshl_add_u64 v[6:7], v[0:1], 0, s[0:1]
	s_mov_b64 s[0:1], 0
	global_store_dword v[0:1], v2, off offset:96

; template <int MODE, bool SWAP, int MT>
; DI void gemm_tile(const int wv_, const Params& p, const u16* __restrict__ A, const u16* __restrict__ Bt, int brow, int bcol, char* smem, const float* gnext) {
;     ...
;   for (int t = 0; t < 32; ++t) {
;     asm volatile("s_waitcnt vmcnt(0)" ::: "memory");
;     __syncthreads();
;     if (t + 1 < 32) stage(t + 1, (t + 1) & 1);
;     const char* sA = smem + (t & 1) * 24576; const char* sB = sA + 16384;
;     bf16x8 Af[MT], Bf[4];
; #pragma unroll
;     for (int n = 0; n < 4; ++n) Bf[n] = *(const bf16x8*)(sB + (wc * 64 + n * 16 + fr) * 64 + fq * 16);
;     constexpr int MH = MT >= 2 ? MT / 2 : 1;
; #pragma unroll
;     for (int m = 0; m < MH; ++m) Af[m] = *(const bf16x8*)(sA + (wr * (16 * MT) + m * 16 + fr) * 64 + fq * 16);
;     __builtin_amdgcn_sched_barrier(0);
; #pragma unroll
;     for (int m = MH; m < MT; ++m) Af[m] = *(const bf16x8*)(sA + (wr * (16 * MT) + m * 16 + fr) * 64 + fq * 16);
; #pragma unroll
;     for (int m = 0; m < MH; ++m)
; #pragma unroll
;       for (int n = 0; n < 4; ++n)
;         acc[m][n] = SWAP ? __builtin_amdgcn_mfma_f32_16x16x32_bf16(Bf[n], Af[m], acc[m][n], 0, 0, 0)
;                          : __builtin_amdgcn_mfma_f32_16x16x32_bf16(Af[m], Bf[n], acc[m][n], 0, 0, 0);
;     __builtin_amdgcn_sched_barrier(0);
; #pragma unroll
;     for (int m = MH; m < MT; ++m)
; #pragma unroll
;       for (int n = 0; n < 4; ++n)
;         acc[m][n] = SWAP ? __builtin_amdgcn_mfma_f32_16x16x32_bf16(Bf[n], Af[m], acc[m][n], 0, 0, 0)
;                          : __builtin_amdgcn_mfma_f32_16x16x32_bf16(Af[m], Bf[n], acc[m][n], 0, 0, 0);
;   }
;     ...
; #pragma unroll
;     for (int m = 0; m < MT; ++m) {
;       int R = brow + wr * (16 * MT) + m * 16 + fq * 4;
;       int b = R / P, pos = R - b * P;
;       const float rs0 = rowscale(p.ss, R), rs1 = rowscale(p.ss, R + 1), rs2 = rowscale(p.ss, R + 2), rs3 = rowscale(p.ss, R + 3);
.LBB0_90:
	s_add_i32 s1, s0, 1
	s_bitcmp1_b32 s1, 0
	s_cselect_b32 s19, 0x6000, 0
	v_add_u32_e32 v2, s19, v76
	v_add_u32_e32 v80, 0x2000, v2
	v_readfirstlane_b32 s19, v2
	s_mov_b32 m0, s19
	v_readfirstlane_b32 s19, v80
	v_add_u32_e32 v2, 0x4000, v2
	s_waitcnt vmcnt(0)
	s_waitcnt vmcnt(0) lgkmcnt(0)
	s_barrier
	global_load_lds_dwordx4 v[0:1], off
	s_mov_b32 m0, s19
	v_readfirstlane_b32 s19, v2
	global_load_lds_dwordx4 v[68:69], off
	s_mov_b32 m0, s19
	s_bitcmp1_b32 s0, 0
	global_load_lds_dwordx4 v[70:71], off
	s_cselect_b32 s0, 0x6000, 0
	v_or_b32_e32 v2, s0, v77
	v_add_u32_e32 v92, v2, v78
	ds_read_b128 v[80:83], v92 offset:16384
	ds_read_b128 v[84:87], v92 offset:17408
	ds_read_b128 v[88:91], v92 offset:18432
	ds_read_b128 v[92:95], v92 offset:19456
	v_add_u32_e32 v2, v2, v79
	ds_read_b128 v[96:99], v2
	ds_read_b128 v[100:103], v2 offset:1024
	s_waitcnt lgkmcnt(0)
	v_mfma_f32_16x16x32_bf16 v[64:67], v[96:99], v[80:83], v[64:67]
	v_mfma_f32_16x16x32_bf16 v[60:63], v[96:99], v[84:87], v[60:63]
	v_mfma_f32_16x16x32_bf16 v[56:59], v[96:99], v[88:91], v[56:59]
	v_mfma_f32_16x16x32_bf16 v[52:55], v[96:99], v[92:95], v[52:55]
	ds_read_b128 v[96:99], v2 offset:2048
	ds_read_b128 v[104:107], v2 offset:3072
	v_mfma_f32_16x16x32_bf16 v[48:51], v[100:103], v[80:83], v[48:51]
	v_mfma_f32_16x16x32_bf16 v[44:47], v[100:103], v[84:87], v[44:47]
	v_mfma_f32_16x16x32_bf16 v[40:43], v[100:103], v[88:91], v[40:43]
	v_mfma_f32_16x16x32_bf16 v[36:39], v[100:103], v[92:95], v[36:39]
	s_waitcnt lgkmcnt(0)
	v_mfma_f32_16x16x32_bf16 v[32:35], v[96:99], v[80:83], v[32:35]
	v_lshl_add_u64 v[0:1], v[0:1], 0, 64
	v_lshl_add_u64 v[68:69], v[68:69], 0, 64
	v_lshl_add_u64 v[70:71], v[70:71], 0, 64
	v_mfma_f32_16x16x32_bf16 v[28:31], v[96:99], v[84:87], v[28:31]
	s_cmp_lg_u32 s1, 31
	s_mov_b32 s0, s1
	v_mfma_f32_16x16x32_bf16 v[24:27], v[96:99], v[88:91], v[24:27]
	v_mfma_f32_16x16x32_bf16 v[20:23], v[96:99], v[92:95], v[20:23]
	v_mfma_f32_16x16x32_bf16 v[16:19], v[104:107], v[80:83], v[16:19]
	v_mfma_f32_16x16x32_bf16 v[12:15], v[104:107], v[84:87], v[12:15]
	v_mfma_f32_16x16x32_bf16 v[8:11], v[104:107], v[88:91], v[8:11]
	v_mfma_f32_16x16x32_bf16 v[4:7], v[104:107], v[92:95], v[4:7]
	s_cbranch_scc1 .LBB0_90
	s_add_i32 s98, s14, s7
	s_cmp_lt_i32 s98, s8
	s_cselect_b32 s98, s98, s14
	s_lshr_b32 s99, s98, 2
	s_mul_i32 s99, s99, 9363
	s_lshr_b32 s99, s99, 16
	s_mul_i32 s100, s99, 28
	s_sub_i32 s100, s98, s100
	s_lshl_b32 s99, s99, 8
	s_sub_i32 s98, s99, s18
	s_add_i32 s98, s98, -1
	s_ashr_i32 s99, s98, 31
	s_lshl_b64 s[98:99], s[98:99], 11
	s_lshl_b32 s100, s100, 7
	s_sub_i32 s100, s100, s15
	s_add_i32 s100, s100, -1
	s_ashr_i32 s101, s100, 31
	s_lshl_b64 s[100:101], s[100:101], 11
	v_lshl_add_u64 v[112:113], v[0:1], 0, s[98:99]
	v_lshl_add_u64 v[114:115], v[68:69], 0, s[98:99]
	v_lshl_add_u64 v[116:117], v[70:71], 0, s[100:101]
	v_add_u32_e32 v0, v77, v79
	v_add_u32_e32 v1, v77, v78
	s_waitcnt vmcnt(0)
	s_waitcnt vmcnt(0)
	s_barrier
	global_load_dword v108, v[112:113], off
	global_load_dword v109, v[114:115], off
	global_load_dword v110, v[116:117], off
	ds_read_b128 v[68:71], v0 offset:25600
	ds_read_b128 v[80:83], v0 offset:24576
	ds_read_b128 v[76:79], v1 offset:44032
	ds_read_b128 v[84:87], v1 offset:43008
	ds_read_b128 v[88:91], v1 offset:41984
	ds_read_b128 v[92:95], v1 offset:40960
	s_waitcnt lgkmcnt(0)
	v_mfma_f32_16x16x32_bf16 v[64:67], v[80:83], v[92:95], v[64:67]
	v_mfma_f32_16x16x32_bf16 v[60:63], v[80:83], v[88:91], v[60:63]
	v_mfma_f32_16x16x32_bf16 v[56:59], v[80:83], v[84:87], v[56:59]
	v_mfma_f32_16x16x32_bf16 v[52:55], v[80:83], v[76:79], v[52:55]
	ds_read_b128 v[80:83], v0 offset:26624
	ds_read_b128 v[96:99], v0 offset:27648
	v_mfma_f32_16x16x32_bf16 v[48:51], v[68:71], v[92:95], v[48:51]
	v_mfma_f32_16x16x32_bf16 v[44:47], v[68:71], v[88:91], v[44:47]
	v_mfma_f32_16x16x32_bf16 v[40:43], v[68:71], v[84:87], v[40:43]
	v_mfma_f32_16x16x32_bf16 v[36:39], v[68:71], v[76:79], v[36:39]
	v_lshl_add_u32 v0, v74, 6, s18
	s_waitcnt lgkmcnt(0)
	v_mfma_f32_16x16x32_bf16 v[16:19], v[96:99], v[92:95], v[16:19]
	s_addk_i32 s15, 0xf600
	s_movk_i32 s19, 0xdf80
	v_mfma_f32_16x16x32_bf16 v[12:15], v[96:99], v[88:91], v[12:15]
	s_barrier
	s_mov_b32 s0, 0x358637bd
	v_mfma_f32_16x16x32_bf16 v[8:11], v[96:99], v[84:87], v[8:11]
	s_mov_b32 s18, 0x3a800000
	s_mov_b32 s20, 0x45800000
	v_mfma_f32_16x16x32_bf16 v[4:7], v[96:99], v[76:79], v[4:7]
	v_lshl_or_b32 v96, v75, 2, v0
	v_lshlrev_b32_e32 v0, 6, v72
	v_or3_b32 v2, v0, s15, v73
	s_mov_b32 s15, 0x7e07e07f
	v_mul_hi_i32 v0, v96, s15
	v_lshrrev_b32_e32 v1, 31, v0
	v_ashrrev_i32_e32 v0, 12, v0
	v_ashrrev_i32_e32 v97, 31, v96
	v_or_b32_e32 v68, 2, v96
	v_add_u32_e32 v70, v0, v1
	v_lshlrev_b64 v[0:1], 6, v[96:97]
	v_ashrrev_i32_e32 v69, 31, v68
	v_lshl_add_u64 v[0:1], s[90:91], 0, v[0:1]
	v_lshlrev_b64 v[68:69], 6, v[68:69]
	v_mfma_f32_16x16x32_bf16 v[32:35], v[80:83], v[92:95], v[32:35]
	v_mad_i32_i24 v98, v70, s19, v96
	v_lshl_add_u64 v[102:103], s[90:91], 0, v[68:69]
	v_lshl_or_b32 v97, v70, 9, v2
	v_mfma_f32_16x16x32_bf16 v[28:31], v[80:83], v[88:91], v[28:31]
	v_ashrrev_i32_e32 v99, 31, v98
	v_mfma_f32_16x16x32_bf16 v[24:27], v[80:83], v[84:87], v[24:27]
	v_mfma_f32_16x16x32_bf16 v[20:23], v[80:83], v[76:79], v[20:23]
	global_load_dwordx4 v[68:71], v[0:1], off offset:112
	global_load_dwordx4 v[72:75], v[0:1], off offset:48
	global_load_dwordx4 v[76:79], v[0:1], off offset:96
	global_load_dwordx4 v[80:83], v[0:1], off offset:32
	global_load_dwordx4 v[84:87], v[0:1], off offset:80
	global_load_dwordx4 v[88:91], v[0:1], off offset:16
	global_load_dwordx4 v[92:95], v[0:1], off offset:64
	global_load_dwordx4 v[104:107], v[0:1], off
	s_waitcnt vmcnt(1)
; DI unsigned pack2(float a, float b) { f32x2_t v = {a, b}; return __builtin_bit_cast(unsigned, __builtin_convertvector(v, bf16x2_t)); }
; template <int MODE, bool SWAP, int MT>
; DI void gemm_tile(const int wv_, const Params& p, const u16* __restrict__ A, const u16* __restrict__ Bt, int brow, int bcol, char* smem, const float* gnext) {
;     ...
;       int R = brow + wr * (16 * MT) + m * 16 + fq * 4;
;       int b = R / P, pos = R - b * P;
;       const float rs0 = rowscale(p.ss, R), rs1 = rowscale(p.ss, R + 1), rs2 = rowscale(p.ss, R + 2), rs3 = rowscale(p.ss, R + 3);
; #pragma unroll
;       for (int n = 0; n < 4; ++n) {
;         int col = bcol + wc * 64 + n * 16 + fr - 2560;
;         uint2 o; o.x = pack2(acc[m][n][0] * rs0, acc[m][n][1] * rs1); o.y = pack2(acc[m][n][2] * rs2, acc[m][n][3] * rs3);
;         *(uint2*)(p.vt + ((size_t)(b * 512 + col)) * P + pos) = o;
	v_mov_b32_e32 v1, v92
	s_waitcnt vmcnt(0)
	v_mov_b32_e32 v0, v104
	v_mov_b32_e32 v92, v105
	v_pk_add_f32 v[0:1], v[0:1], v[92:93]
	v_mov_b32_e32 v92, v106
	v_mov_b32_e32 v93, v94
	v_mov_b32_e32 v94, v107
	v_pk_add_f32 v[92:93], v[92:93], v[94:95]
	s_nop 0
	v_pk_add_f32 v[0:1], v[0:1], v[92:93]
	v_mov_b32_e32 v92, v88
	v_mov_b32_e32 v93, v84
	v_mov_b32_e32 v84, v89
	v_mov_b32_e32 v88, v90
	v_mov_b32_e32 v89, v86
	v_mov_b32_e32 v86, v91
	v_pk_add_f32 v[84:85], v[92:93], v[84:85]
	v_pk_add_f32 v[86:87], v[88:89], v[86:87]
	s_nop 0
	v_pk_add_f32 v[84:85], v[84:85], v[86:87]
	s_nop 0
	v_pk_add_f32 v[0:1], v[0:1], v[84:85]
	v_mov_b32_e32 v84, v80
	v_mov_b32_e32 v85, v76
	v_mov_b32_e32 v76, v81
	v_mov_b32_e32 v80, v82
	v_mov_b32_e32 v81, v78
	v_mov_b32_e32 v78, v83
	v_pk_add_f32 v[76:77], v[84:85], v[76:77]
	v_pk_add_f32 v[78:79], v[80:81], v[78:79]
	s_nop 0
	v_pk_add_f32 v[76:77], v[76:77], v[78:79]
	s_nop 0
	v_pk_add_f32 v[0:1], v[0:1], v[76:77]
	v_mov_b32_e32 v76, v72
	v_mov_b32_e32 v77, v68
	v_mov_b32_e32 v68, v73
	v_mov_b32_e32 v72, v74
	v_mov_b32_e32 v73, v70
	v_mov_b32_e32 v70, v75
	v_pk_add_f32 v[68:69], v[76:77], v[68:69]
	v_pk_add_f32 v[70:71], v[72:73], v[70:71]
	s_nop 0
	v_pk_add_f32 v[68:69], v[68:69], v[70:71]
	s_nop 0
	v_pk_add_f32 v[68:69], v[0:1], v[68:69]
	v_mov_b64_e32 v[0:1], s[0:1]
	v_pk_fma_f32 v[68:69], v[68:69], s[18:19], v[0:1] op_sel_hi:[1,0,0]
	s_nop 0
	v_mul_f32_e32 v70, 0x4b800000, v68
	v_cmp_gt_f32_e64 s[0:1], s96, v68
	v_cmp_gt_f32_e32 vcc, s96, v69
	s_nop 0
	v_cndmask_b32_e64 v68, v68, v70, s[0:1]
	v_mul_f32_e32 v70, 0x4b800000, v69
	v_cndmask_b32_e32 v69, v69, v70, vcc
	v_rsq_f32_e32 v68, v68
	v_rsq_f32_e32 v69, v69
	s_nop 0
	v_pk_mul_f32 v[70:71], v[68:69], s[20:21] op_sel_hi:[1,0]
	s_nop 0
	v_cndmask_b32_e32 v101, v69, v71, vcc
	v_cndmask_b32_e64 v100, v68, v70, s[0:1]
	global_load_dwordx4 v[68:71], v[102:103], off offset:112
	global_load_dwordx4 v[72:75], v[102:103], off offset:48
	global_load_dwordx4 v[76:79], v[102:103], off offset:96
	global_load_dwordx4 v[80:83], v[102:103], off offset:32
	global_load_dwordx4 v[84:87], v[102:103], off offset:80
	global_load_dwordx4 v[88:91], v[102:103], off offset:16
	global_load_dwordx4 v[92:95], v[102:103], off offset:64
	s_nop 0
	global_load_dwordx4 v[102:105], v[102:103], off
	v_pk_mul_f32 v[64:65], v[64:65], v[100:101]
	v_pk_mul_f32 v[52:53], v[52:53], v[100:101]
	v_cvt_pk_bf16_f32 v64, v64, v65
	v_cvt_pk_bf16_f32 v52, v52, v53
	v_pk_mul_f32 v[60:61], v[60:61], v[100:101]
	v_pk_mul_f32 v[56:57], v[56:57], v[100:101]
	v_cvt_pk_bf16_f32 v60, v60, v61
	v_cvt_pk_bf16_f32 v56, v56, v57
	s_waitcnt vmcnt(1)
	v_mov_b32_e32 v107, v92
	s_waitcnt vmcnt(0)
	v_mov_b32_e32 v106, v102
	v_mov_b32_e32 v92, v103
	v_mov_b32_e32 v102, v104
	v_mov_b32_e32 v103, v94
	v_mov_b32_e32 v94, v105
	v_pk_add_f32 v[92:93], v[106:107], v[92:93]
	v_pk_add_f32 v[94:95], v[102:103], v[94:95]
	s_nop 0
	v_pk_add_f32 v[92:93], v[92:93], v[94:95]
	v_mov_b32_e32 v94, v88
	v_mov_b32_e32 v95, v84
	v_mov_b32_e32 v84, v89
	v_mov_b32_e32 v88, v90
	v_mov_b32_e32 v89, v86
	v_mov_b32_e32 v86, v91
	v_pk_add_f32 v[84:85], v[94:95], v[84:85]
	v_pk_add_f32 v[86:87], v[88:89], v[86:87]
	s_nop 0
	v_pk_add_f32 v[84:85], v[84:85], v[86:87]
	v_mov_b32_e32 v86, v80
	v_mov_b32_e32 v87, v76
	v_mov_b32_e32 v76, v81
	v_mov_b32_e32 v80, v82
	v_mov_b32_e32 v81, v78
	v_mov_b32_e32 v78, v83
	v_pk_add_f32 v[76:77], v[86:87], v[76:77]
	v_pk_add_f32 v[78:79], v[80:81], v[78:79]
	v_pk_add_f32 v[84:85], v[92:93], v[84:85]
	v_pk_add_f32 v[76:77], v[76:77], v[78:79]
	v_mov_b32_e32 v78, v72
	v_mov_b32_e32 v79, v68
	v_mov_b32_e32 v68, v73
	v_mov_b32_e32 v72, v74
	v_mov_b32_e32 v73, v70
	v_mov_b32_e32 v70, v75
	v_pk_add_f32 v[68:69], v[78:79], v[68:69]
	v_pk_add_f32 v[70:71], v[72:73], v[70:71]
	v_pk_add_f32 v[76:77], v[84:85], v[76:77]
	v_pk_add_f32 v[68:69], v[68:69], v[70:71]
	v_mov_b64_e32 v[84:85], s[72:73]
	v_pk_add_f32 v[68:69], v[76:77], v[68:69]
	s_nop 0
	v_pk_fma_f32 v[68:69], v[68:69], s[18:19], v[0:1] op_sel_hi:[1,0,0]
	s_nop 0
	v_mul_f32_e32 v65, 0x4b800000, v68
	v_cmp_gt_f32_e64 s[0:1], s96, v68
	v_cmp_gt_f32_e32 vcc, s96, v69
	s_nop 0
	v_cndmask_b32_e64 v65, v68, v65, s[0:1]
	v_rsq_f32_e32 v68, v65
	v_mul_f32_e32 v65, 0x4b800000, v69
	v_cndmask_b32_e32 v65, v69, v65, vcc
	v_rsq_f32_e32 v69, v65
	s_nop 0
	v_pk_mul_f32 v[70:71], v[68:69], s[20:21] op_sel_hi:[1,0]
	s_nop 0
	v_cndmask_b32_e32 v69, v69, v71, vcc
	v_cndmask_b32_e64 v68, v68, v70, s[0:1]
	v_pk_mul_f32 v[54:55], v[54:55], v[68:69]
	s_movk_i32 s21, 0x4100
	v_cvt_pk_bf16_f32 v53, v54, v55
	v_or_b32_e32 v54, 48, v97
	v_lshlrev_b64 v[70:71], 1, v[98:99]
	v_mad_i64_i32 v[54:55], s[0:1], v54, s21, v[84:85]
	v_lshl_add_u64 v[54:55], v[54:55], 0, v[70:71]
	global_store_dwordx2 v[54:55], v[52:53], off
	v_or_b32_e32 v52, 16, v96
	v_mul_hi_i32 v53, v52, s15
	v_lshrrev_b32_e32 v54, 31, v53
	v_ashrrev_i32_e32 v53, 12, v53
	v_pk_mul_f32 v[62:63], v[62:63], v[68:69]
	v_pk_mul_f32 v[58:59], v[58:59], v[68:69]
	v_add_u32_e32 v54, v53, v54
	v_ashrrev_i32_e32 v53, 31, v52
	v_pk_mul_f32 v[66:67], v[66:67], v[68:69]
	v_cvt_pk_bf16_f32 v61, v62, v63
	v_or_b32_e32 v62, 16, v97
	v_cvt_pk_bf16_f32 v57, v58, v59
	v_or_b32_e32 v58, 32, v97
	v_mad_i32_i24 v86, v54, s19, v52
	v_lshlrev_b64 v[52:53], 6, v[52:53]
	v_cvt_pk_bf16_f32 v65, v66, v67
	v_mad_i64_i32 v[66:67], s[0:1], v97, s21, v[84:85]
	v_mad_i64_i32 v[62:63], s[0:1], v62, s21, v[84:85]
	v_mad_i64_i32 v[58:59], s[0:1], v58, s21, v[84:85]
	v_lshl_add_u64 v[82:83], s[90:91], 0, v[52:53]
	v_or_b32_e32 v52, 18, v96
	v_lshl_add_u64 v[66:67], v[66:67], 0, v[70:71]
	v_lshl_add_u64 v[62:63], v[62:63], 0, v[70:71]
	v_lshl_add_u64 v[58:59], v[58:59], 0, v[70:71]
	v_ashrrev_i32_e32 v53, 31, v52
	global_store_dwordx2 v[66:67], v[64:65], off
	global_store_dwordx2 v[62:63], v[60:61], off
	global_store_dwordx2 v[58:59], v[56:57], off
	v_lshlrev_b64 v[52:53], 6, v[52:53]
	v_lshl_add_u64 v[80:81], s[90:91], 0, v[52:53]
	v_lshl_or_b32 v90, v54, 9, v2
	global_load_dwordx4 v[52:55], v[82:83], off offset:112
	global_load_dwordx4 v[56:59], v[82:83], off offset:48
	global_load_dwordx4 v[60:63], v[82:83], off offset:96
	global_load_dwordx4 v[64:67], v[82:83], off offset:32
	global_load_dwordx4 v[68:71], v[82:83], off offset:80
	global_load_dwordx4 v[72:75], v[82:83], off offset:16
	global_load_dwordx4 v[76:79], v[82:83], off offset:64
	global_load_dwordx4 v[92:95], v[82:83], off
	v_ashrrev_i32_e32 v87, 31, v86
	s_waitcnt vmcnt(1)
; DI unsigned pack2(float a, float b) { f32x2_t v = {a, b}; return __builtin_bit_cast(unsigned, __builtin_convertvector(v, bf16x2_t)); }
; template <int MODE, bool SWAP, int MT>
; DI void gemm_tile(const int wv_, const Params& p, const u16* __restrict__ A, const u16* __restrict__ Bt, int brow, int bcol, char* smem, const float* gnext) {
;     ...
;       int R = brow + wr * (16 * MT) + m * 16 + fq * 4;
;       int b = R / P, pos = R - b * P;
;       const float rs0 = rowscale(p.ss, R), rs1 = rowscale(p.ss, R + 1), rs2 = rowscale(p.ss, R + 2), rs3 = rowscale(p.ss, R + 3);
; #pragma unroll
;       for (int n = 0; n < 4; ++n) {
;         int col = bcol + wc * 64 + n * 16 + fr - 2560;
;         uint2 o; o.x = pack2(acc[m][n][0] * rs0, acc[m][n][1] * rs1); o.y = pack2(acc[m][n][2] * rs2, acc[m][n][3] * rs3);
;         *(uint2*)(p.vt + ((size_t)(b * 512 + col)) * P + pos) = o;
	v_mov_b32_e32 v83, v76
	s_waitcnt vmcnt(0)
	v_mov_b32_e32 v82, v92
	v_mov_b32_e32 v76, v93
	v_pk_add_f32 v[76:77], v[82:83], v[76:77]
	v_mov_b32_e32 v82, v94
	v_mov_b32_e32 v83, v78
	v_mov_b32_e32 v78, v95
	v_pk_add_f32 v[78:79], v[82:83], v[78:79]
	s_nop 0
	v_pk_add_f32 v[76:77], v[76:77], v[78:79]
	v_mov_b32_e32 v78, v72
	v_mov_b32_e32 v79, v68
	v_mov_b32_e32 v68, v73
	v_mov_b32_e32 v72, v74
	v_mov_b32_e32 v73, v70
	v_mov_b32_e32 v70, v75
	v_pk_add_f32 v[68:69], v[78:79], v[68:69]
	v_pk_add_f32 v[70:71], v[72:73], v[70:71]
	s_nop 0
	v_pk_add_f32 v[68:69], v[68:69], v[70:71]
	v_mov_b32_e32 v70, v64
	v_mov_b32_e32 v71, v60
	v_mov_b32_e32 v60, v65
	v_mov_b32_e32 v64, v66
	v_mov_b32_e32 v65, v62
	v_mov_b32_e32 v62, v67
	v_pk_add_f32 v[60:61], v[70:71], v[60:61]
	v_pk_add_f32 v[62:63], v[64:65], v[62:63]
	v_pk_add_f32 v[68:69], v[76:77], v[68:69]
	v_pk_add_f32 v[60:61], v[60:61], v[62:63]
	v_mov_b32_e32 v62, v56
	v_mov_b32_e32 v63, v52
	v_mov_b32_e32 v52, v57
	v_mov_b32_e32 v56, v58
	v_mov_b32_e32 v57, v54
	v_mov_b32_e32 v54, v59
	v_pk_add_f32 v[52:53], v[62:63], v[52:53]
	v_pk_add_f32 v[54:55], v[56:57], v[54:55]
	v_pk_add_f32 v[60:61], v[68:69], v[60:61]
	v_pk_add_f32 v[52:53], v[52:53], v[54:55]
	s_nop 0
	v_pk_add_f32 v[52:53], v[60:61], v[52:53]
	s_nop 0
	v_pk_fma_f32 v[52:53], v[52:53], s[18:19], v[0:1] op_sel_hi:[1,0,0]
	s_nop 0
	v_mul_f32_e32 v54, 0x4b800000, v52
	v_cmp_gt_f32_e64 s[0:1], s96, v52
	v_cmp_gt_f32_e32 vcc, s96, v53
	s_nop 0
	v_cndmask_b32_e64 v52, v52, v54, s[0:1]
	v_mul_f32_e32 v54, 0x4b800000, v53
	v_cndmask_b32_e32 v53, v53, v54, vcc
	v_rsq_f32_e32 v52, v52
	v_rsq_f32_e32 v53, v53
	s_nop 0
	v_pk_mul_f32 v[54:55], v[52:53], s[20:21] op_sel_hi:[1,0]
	s_nop 0
	v_cndmask_b32_e32 v89, v53, v55, vcc
	v_cndmask_b32_e64 v88, v52, v54, s[0:1]
	global_load_dwordx4 v[52:55], v[80:81], off offset:112
	global_load_dwordx4 v[56:59], v[80:81], off offset:48
	global_load_dwordx4 v[60:63], v[80:81], off offset:96
	global_load_dwordx4 v[64:67], v[80:81], off offset:32
	global_load_dwordx4 v[68:71], v[80:81], off offset:80
	global_load_dwordx4 v[72:75], v[80:81], off offset:16
	global_load_dwordx4 v[76:79], v[80:81], off offset:64
	s_nop 0
	global_load_dwordx4 v[80:83], v[80:81], off
	v_pk_mul_f32 v[48:49], v[48:49], v[88:89]
	v_pk_mul_f32 v[36:37], v[36:37], v[88:89]
	v_cvt_pk_bf16_f32 v48, v48, v49
	v_cvt_pk_bf16_f32 v36, v36, v37
	v_pk_mul_f32 v[44:45], v[44:45], v[88:89]
	v_pk_mul_f32 v[40:41], v[40:41], v[88:89]
	v_cvt_pk_bf16_f32 v44, v44, v45
	v_cvt_pk_bf16_f32 v40, v40, v41
	s_waitcnt vmcnt(1)
	v_mov_b32_e32 v93, v76
	s_waitcnt vmcnt(0)
	v_mov_b32_e32 v92, v80
	v_mov_b32_e32 v76, v81
	v_mov_b32_e32 v80, v82
	v_mov_b32_e32 v81, v78
	v_mov_b32_e32 v78, v83
	v_pk_add_f32 v[76:77], v[92:93], v[76:77]
	v_pk_add_f32 v[78:79], v[80:81], v[78:79]
	s_nop 0
	v_pk_add_f32 v[76:77], v[76:77], v[78:79]
	v_mov_b32_e32 v78, v72
	v_mov_b32_e32 v79, v68
	v_mov_b32_e32 v68, v73
	v_mov_b32_e32 v72, v74
	v_mov_b32_e32 v73, v70
	v_mov_b32_e32 v70, v75
	v_pk_add_f32 v[68:69], v[78:79], v[68:69]
	v_pk_add_f32 v[70:71], v[72:73], v[70:71]
	s_nop 0
	v_pk_add_f32 v[68:69], v[68:69], v[70:71]
	v_mov_b32_e32 v70, v64
	v_mov_b32_e32 v71, v60
	v_mov_b32_e32 v60, v65
	v_mov_b32_e32 v64, v66
	v_mov_b32_e32 v65, v62
	v_mov_b32_e32 v62, v67
	v_pk_add_f32 v[60:61], v[70:71], v[60:61]
	v_pk_add_f32 v[62:63], v[64:65], v[62:63]
	v_pk_add_f32 v[68:69], v[76:77], v[68:69]
	v_pk_add_f32 v[60:61], v[60:61], v[62:63]
	v_mov_b32_e32 v62, v56
	v_mov_b32_e32 v63, v52
	v_mov_b32_e32 v52, v57
	v_mov_b32_e32 v56, v58
	v_mov_b32_e32 v57, v54
	v_mov_b32_e32 v54, v59
	v_pk_add_f32 v[52:53], v[62:63], v[52:53]
	v_pk_add_f32 v[54:55], v[56:57], v[54:55]
	v_pk_add_f32 v[60:61], v[68:69], v[60:61]
	v_pk_add_f32 v[52:53], v[52:53], v[54:55]
	s_nop 0
	v_pk_add_f32 v[52:53], v[60:61], v[52:53]
	s_nop 0
	v_pk_fma_f32 v[52:53], v[52:53], s[18:19], v[0:1] op_sel_hi:[1,0,0]
	s_nop 0
	v_mul_f32_e32 v49, 0x4b800000, v52
	v_cmp_gt_f32_e64 s[0:1], s96, v52
	v_cmp_gt_f32_e32 vcc, s96, v53
	s_nop 0
	v_cndmask_b32_e64 v49, v52, v49, s[0:1]
	v_rsq_f32_e32 v52, v49
	v_mul_f32_e32 v49, 0x4b800000, v53
	v_cndmask_b32_e32 v49, v53, v49, vcc
	v_rsq_f32_e32 v53, v49
	s_nop 0
	v_pk_mul_f32 v[54:55], v[52:53], s[20:21] op_sel_hi:[1,0]
	s_nop 0
	v_cndmask_b32_e32 v53, v53, v55, vcc
	v_cndmask_b32_e64 v52, v52, v54, s[0:1]
	v_pk_mul_f32 v[38:39], v[38:39], v[52:53]
	v_lshlrev_b64 v[54:55], 1, v[86:87]
	v_cvt_pk_bf16_f32 v37, v38, v39
	v_or_b32_e32 v38, 48, v90
	v_mad_i64_i32 v[38:39], s[0:1], v38, s21, v[84:85]
	v_lshl_add_u64 v[38:39], v[38:39], 0, v[54:55]
	global_store_dwordx2 v[38:39], v[36:37], off
	v_or_b32_e32 v36, 32, v96
	v_mul_hi_i32 v37, v36, s15
	v_lshrrev_b32_e32 v38, 31, v37
	v_ashrrev_i32_e32 v37, 12, v37
	v_pk_mul_f32 v[46:47], v[46:47], v[52:53]
	v_pk_mul_f32 v[42:43], v[42:43], v[52:53]
	v_add_u32_e32 v38, v37, v38
	v_ashrrev_i32_e32 v37, 31, v36
	v_pk_mul_f32 v[50:51], v[50:51], v[52:53]
	v_cvt_pk_bf16_f32 v45, v46, v47
	v_or_b32_e32 v46, 16, v90
	v_cvt_pk_bf16_f32 v41, v42, v43
	v_or_b32_e32 v42, 32, v90
	v_mad_i32_i24 v68, v38, s19, v36
	v_lshlrev_b64 v[36:37], 6, v[36:37]
	v_cvt_pk_bf16_f32 v49, v50, v51
	v_mad_i64_i32 v[50:51], s[0:1], v90, s21, v[84:85]
	v_mad_i64_i32 v[46:47], s[0:1], v46, s21, v[84:85]
	v_mad_i64_i32 v[42:43], s[0:1], v42, s21, v[84:85]
	v_lshl_add_u64 v[66:67], s[90:91], 0, v[36:37]
	v_or_b32_e32 v36, 34, v96
	v_lshl_add_u64 v[50:51], v[50:51], 0, v[54:55]
	v_lshl_add_u64 v[46:47], v[46:47], 0, v[54:55]
	v_lshl_add_u64 v[42:43], v[42:43], 0, v[54:55]
	v_ashrrev_i32_e32 v37, 31, v36
	global_store_dwordx2 v[50:51], v[48:49], off
	global_store_dwordx2 v[46:47], v[44:45], off
	global_store_dwordx2 v[42:43], v[40:41], off
	v_lshlrev_b64 v[36:37], 6, v[36:37]
	v_lshl_add_u64 v[64:65], s[90:91], 0, v[36:37]
	v_lshl_or_b32 v72, v38, 9, v2
	global_load_dwordx4 v[36:39], v[66:67], off offset:112
	global_load_dwordx4 v[40:43], v[66:67], off offset:48
	global_load_dwordx4 v[44:47], v[66:67], off offset:96
	global_load_dwordx4 v[48:51], v[66:67], off offset:32
	global_load_dwordx4 v[52:55], v[66:67], off offset:80
	global_load_dwordx4 v[56:59], v[66:67], off offset:16
	global_load_dwordx4 v[60:63], v[66:67], off offset:64
	global_load_dwordx4 v[74:77], v[66:67], off
	v_ashrrev_i32_e32 v69, 31, v68
	s_waitcnt vmcnt(1)
; DI unsigned pack2(float a, float b) { f32x2_t v = {a, b}; return __builtin_bit_cast(unsigned, __builtin_convertvector(v, bf16x2_t)); }
; template <int MODE, bool SWAP, int MT>
; DI void gemm_tile(const int wv_, const Params& p, const u16* __restrict__ A, const u16* __restrict__ Bt, int brow, int bcol, char* smem, const float* gnext) {
;     ...
;       int R = brow + wr * (16 * MT) + m * 16 + fq * 4;
;       int b = R / P, pos = R - b * P;
;       const float rs0 = rowscale(p.ss, R), rs1 = rowscale(p.ss, R + 1), rs2 = rowscale(p.ss, R + 2), rs3 = rowscale(p.ss, R + 3);
; #pragma unroll
;       for (int n = 0; n < 4; ++n) {
;         int col = bcol + wc * 64 + n * 16 + fr - 2560;
;         uint2 o; o.x = pack2(acc[m][n][0] * rs0, acc[m][n][1] * rs1); o.y = pack2(acc[m][n][2] * rs2, acc[m][n][3] * rs3);
;         *(uint2*)(p.vt + ((size_t)(b * 512 + col)) * P + pos) = o;
	v_mov_b32_e32 v67, v60
	s_waitcnt vmcnt(0)
	v_mov_b32_e32 v66, v74
	v_mov_b32_e32 v60, v75
	v_pk_add_f32 v[60:61], v[66:67], v[60:61]
	v_mov_b32_e32 v66, v76
	v_mov_b32_e32 v67, v62
	v_mov_b32_e32 v62, v77
	v_pk_add_f32 v[62:63], v[66:67], v[62:63]
	s_nop 0
	v_pk_add_f32 v[60:61], v[60:61], v[62:63]
	v_mov_b32_e32 v62, v56
	v_mov_b32_e32 v63, v52
	v_mov_b32_e32 v52, v57
	v_mov_b32_e32 v56, v58
	v_mov_b32_e32 v57, v54
	v_mov_b32_e32 v54, v59
	v_pk_add_f32 v[52:53], v[62:63], v[52:53]
	v_pk_add_f32 v[54:55], v[56:57], v[54:55]
	s_nop 0
	v_pk_add_f32 v[52:53], v[52:53], v[54:55]
	v_mov_b32_e32 v54, v48
	v_mov_b32_e32 v55, v44
	v_mov_b32_e32 v44, v49
	v_mov_b32_e32 v48, v50
	v_mov_b32_e32 v49, v46
	v_mov_b32_e32 v46, v51
	v_pk_add_f32 v[44:45], v[54:55], v[44:45]
	v_pk_add_f32 v[46:47], v[48:49], v[46:47]
	v_pk_add_f32 v[52:53], v[60:61], v[52:53]
	v_pk_add_f32 v[44:45], v[44:45], v[46:47]
	v_mov_b32_e32 v46, v40
	v_mov_b32_e32 v47, v36
	v_mov_b32_e32 v36, v41
	v_mov_b32_e32 v40, v42
	v_mov_b32_e32 v41, v38
	v_mov_b32_e32 v38, v43
	v_pk_add_f32 v[36:37], v[46:47], v[36:37]
	v_pk_add_f32 v[38:39], v[40:41], v[38:39]
	v_pk_add_f32 v[44:45], v[52:53], v[44:45]
	v_pk_add_f32 v[36:37], v[36:37], v[38:39]
	s_nop 0
	v_pk_add_f32 v[36:37], v[44:45], v[36:37]
	s_nop 0
	v_pk_fma_f32 v[36:37], v[36:37], s[18:19], v[0:1] op_sel_hi:[1,0,0]
	s_nop 0
	v_mul_f32_e32 v38, 0x4b800000, v36
	v_cmp_gt_f32_e64 s[0:1], s96, v36
	v_cmp_gt_f32_e32 vcc, s96, v37
	s_nop 0
	v_cndmask_b32_e64 v36, v36, v38, s[0:1]
	v_mul_f32_e32 v38, 0x4b800000, v37
	v_cndmask_b32_e32 v37, v37, v38, vcc
	v_rsq_f32_e32 v36, v36
	v_rsq_f32_e32 v37, v37
	s_nop 0
	v_pk_mul_f32 v[38:39], v[36:37], s[20:21] op_sel_hi:[1,0]
	s_nop 0
	v_cndmask_b32_e32 v71, v37, v39, vcc
	v_cndmask_b32_e64 v70, v36, v38, s[0:1]
	global_load_dwordx4 v[36:39], v[64:65], off offset:112
	global_load_dwordx4 v[40:43], v[64:65], off offset:48
	global_load_dwordx4 v[44:47], v[64:65], off offset:96
	global_load_dwordx4 v[48:51], v[64:65], off offset:32
	global_load_dwordx4 v[52:55], v[64:65], off offset:80
	global_load_dwordx4 v[56:59], v[64:65], off offset:16
	global_load_dwordx4 v[60:63], v[64:65], off offset:64
	s_nop 0
	global_load_dwordx4 v[64:67], v[64:65], off
	v_pk_mul_f32 v[32:33], v[32:33], v[70:71]
	v_pk_mul_f32 v[20:21], v[20:21], v[70:71]
	v_cvt_pk_bf16_f32 v32, v32, v33
	v_cvt_pk_bf16_f32 v20, v20, v21
	v_pk_mul_f32 v[28:29], v[28:29], v[70:71]
	v_pk_mul_f32 v[24:25], v[24:25], v[70:71]
	v_cvt_pk_bf16_f32 v28, v28, v29
	v_cvt_pk_bf16_f32 v24, v24, v25
	s_waitcnt vmcnt(1)
	v_mov_b32_e32 v75, v60
	s_waitcnt vmcnt(0)
	v_mov_b32_e32 v74, v64
	v_mov_b32_e32 v60, v65
	v_mov_b32_e32 v64, v66
	v_mov_b32_e32 v65, v62
	v_mov_b32_e32 v62, v67
	v_pk_add_f32 v[60:61], v[74:75], v[60:61]
	v_pk_add_f32 v[62:63], v[64:65], v[62:63]
	s_nop 0
	v_pk_add_f32 v[60:61], v[60:61], v[62:63]
	v_mov_b32_e32 v62, v56
	v_mov_b32_e32 v63, v52
	v_mov_b32_e32 v52, v57
	v_mov_b32_e32 v56, v58
	v_mov_b32_e32 v57, v54
	v_mov_b32_e32 v54, v59
	v_pk_add_f32 v[52:53], v[62:63], v[52:53]
	v_pk_add_f32 v[54:55], v[56:57], v[54:55]
	s_nop 0
	v_pk_add_f32 v[52:53], v[52:53], v[54:55]
	v_mov_b32_e32 v54, v48
	v_mov_b32_e32 v55, v44
	v_mov_b32_e32 v44, v49
	v_mov_b32_e32 v48, v50
	v_mov_b32_e32 v49, v46
	v_mov_b32_e32 v46, v51
	v_pk_add_f32 v[44:45], v[54:55], v[44:45]
	v_pk_add_f32 v[46:47], v[48:49], v[46:47]
	v_pk_add_f32 v[52:53], v[60:61], v[52:53]
	v_pk_add_f32 v[44:45], v[44:45], v[46:47]
	v_mov_b32_e32 v46, v40
	v_mov_b32_e32 v47, v36
	v_mov_b32_e32 v36, v41
	v_mov_b32_e32 v40, v42
	v_mov_b32_e32 v41, v38
	v_mov_b32_e32 v38, v43
	v_pk_add_f32 v[36:37], v[46:47], v[36:37]
	v_pk_add_f32 v[38:39], v[40:41], v[38:39]
	v_pk_add_f32 v[44:45], v[52:53], v[44:45]
	v_pk_add_f32 v[36:37], v[36:37], v[38:39]
	s_nop 0
	v_pk_add_f32 v[36:37], v[44:45], v[36:37]
	s_nop 0
	v_pk_fma_f32 v[36:37], v[36:37], s[18:19], v[0:1] op_sel_hi:[1,0,0]
	s_nop 0
	v_mul_f32_e32 v33, 0x4b800000, v36
	v_cmp_gt_f32_e64 s[0:1], s96, v36
	v_cmp_gt_f32_e32 vcc, s96, v37
	s_nop 0
	v_cndmask_b32_e64 v33, v36, v33, s[0:1]
	v_rsq_f32_e32 v36, v33
	v_mul_f32_e32 v33, 0x4b800000, v37
	v_cndmask_b32_e32 v33, v37, v33, vcc
	v_rsq_f32_e32 v37, v33
	s_nop 0
	v_pk_mul_f32 v[38:39], v[36:37], s[20:21] op_sel_hi:[1,0]
	s_nop 0
	v_cndmask_b32_e32 v37, v37, v39, vcc
	v_cndmask_b32_e64 v36, v36, v38, s[0:1]
	v_pk_mul_f32 v[22:23], v[22:23], v[36:37]
	v_lshlrev_b64 v[38:39], 1, v[68:69]
	v_cvt_pk_bf16_f32 v21, v22, v23
	v_or_b32_e32 v22, 48, v72
	v_mad_i64_i32 v[22:23], s[0:1], v22, s21, v[84:85]
	v_lshl_add_u64 v[22:23], v[22:23], 0, v[38:39]
	global_store_dwordx2 v[22:23], v[20:21], off
	v_or_b32_e32 v20, 48, v96
	v_mul_hi_i32 v21, v20, s15
	v_lshrrev_b32_e32 v22, 31, v21
	v_ashrrev_i32_e32 v21, 12, v21
	v_add_u32_e32 v40, v21, v22
	v_ashrrev_i32_e32 v21, 31, v20
	v_pk_mul_f32 v[30:31], v[30:31], v[36:37]
	v_pk_mul_f32 v[26:27], v[26:27], v[36:37]
	v_mad_i32_i24 v52, v40, s19, v20
	v_lshlrev_b64 v[20:21], 6, v[20:21]
	v_pk_mul_f32 v[34:35], v[34:35], v[36:37]
	v_cvt_pk_bf16_f32 v29, v30, v31
	v_or_b32_e32 v30, 16, v72
	v_cvt_pk_bf16_f32 v25, v26, v27
	v_or_b32_e32 v26, 32, v72
	v_lshl_add_u64 v[48:49], s[90:91], 0, v[20:21]
	v_or_b32_e32 v20, 50, v96
	v_cvt_pk_bf16_f32 v33, v34, v35
	v_mad_i64_i32 v[34:35], s[0:1], v72, s21, v[84:85]
	v_mad_i64_i32 v[30:31], s[0:1], v30, s21, v[84:85]
	v_mad_i64_i32 v[26:27], s[0:1], v26, s21, v[84:85]
	v_ashrrev_i32_e32 v21, 31, v20
	v_lshl_add_u64 v[34:35], v[34:35], 0, v[38:39]
	v_lshl_add_u64 v[30:31], v[30:31], 0, v[38:39]
	v_lshl_add_u64 v[26:27], v[26:27], 0, v[38:39]
	v_lshlrev_b64 v[20:21], 6, v[20:21]
	global_store_dwordx2 v[34:35], v[32:33], off
	global_store_dwordx2 v[30:31], v[28:29], off
	global_store_dwordx2 v[26:27], v[24:25], off
	v_lshl_add_u64 v[32:33], s[90:91], 0, v[20:21]
	global_load_dwordx4 v[20:23], v[32:33], off offset:48
	global_load_dwordx4 v[24:27], v[32:33], off offset:16
	global_load_dwordx4 v[28:31], v[32:33], off
	s_nop 0
	global_load_dwordx4 v[32:35], v[32:33], off offset:32
	v_lshl_or_b32 v2, v40, 9, v2
	v_ashrrev_i32_e32 v53, 31, v52
	s_waitcnt vmcnt(3)
; DI unsigned pack2(float a, float b) { f32x2_t v = {a, b}; return __builtin_bit_cast(unsigned, __builtin_convertvector(v, bf16x2_t)); }
; template <int MODE, bool SWAP, int MT>
; DI void gemm_tile(const int wv_, const Params& p, const u16* __restrict__ A, const u16* __restrict__ Bt, int brow, int bcol, char* smem, const float* gnext) {
;     ...
;       int R = brow + wr * (16 * MT) + m * 16 + fq * 4;
;       int b = R / P, pos = R - b * P;
;       const float rs0 = rowscale(p.ss, R), rs1 = rowscale(p.ss, R + 1), rs2 = rowscale(p.ss, R + 2), rs3 = rowscale(p.ss, R + 3);
; #pragma unroll
;       for (int n = 0; n < 4; ++n) {
;         int col = bcol + wc * 64 + n * 16 + fr - 2560;
;         uint2 o; o.x = pack2(acc[m][n][0] * rs0, acc[m][n][1] * rs1); o.y = pack2(acc[m][n][2] * rs2, acc[m][n][3] * rs3);
;         *(uint2*)(p.vt + ((size_t)(b * 512 + col)) * P + pos) = o;
;       }
;     }
	v_mov_b32_e32 v37, v22
	v_mov_b32_e32 v36, v21
	s_waitcnt vmcnt(1)
	v_mov_b32_e32 v22, v29
	v_pk_add_f32 v[28:29], v[28:29], v[22:23]
	v_mov_b32_e32 v22, v31
	v_pk_add_f32 v[30:31], v[30:31], v[22:23]
	v_mov_b32_e32 v22, v25
	v_mov_b32_e32 v21, v23
	v_pk_add_f32 v[24:25], v[24:25], v[22:23]
	v_mov_b32_e32 v22, v27
	v_pk_add_f32 v[20:21], v[36:37], v[20:21]
	v_pk_add_f32 v[26:27], v[26:27], v[22:23]
	v_pk_add_f32 v[56:57], v[20:21], v[20:21] op_sel:[0,1] op_sel_hi:[1,0]
	v_or_b32_e32 v20, 51, v96
	s_waitcnt vmcnt(0)
	v_mov_b32_e32 v29, v32
	v_mov_b32_e32 v31, v33
	v_mov_b32_e32 v25, v34
	v_mov_b32_e32 v27, v35
	v_ashrrev_i32_e32 v21, 31, v20
	v_pk_add_f32 v[28:29], v[28:29], v[30:31]
	v_pk_add_f32 v[24:25], v[24:25], v[26:27]
	v_lshlrev_b64 v[20:21], 6, v[20:21]
	v_pk_add_f32 v[24:25], v[28:29], v[24:25]
	v_lshl_add_u64 v[32:33], s[90:91], 0, v[20:21]
	v_pk_add_f32 v[54:55], v[24:25], v[24:25] op_sel:[0,1] op_sel_hi:[1,0]
	global_load_dwordx4 v[20:23], v[32:33], off offset:32
	global_load_dwordx4 v[24:27], v[32:33], off offset:16
	global_load_dwordx4 v[28:31], v[32:33], off
	s_nop 0
	global_load_dwordx4 v[32:35], v[32:33], off offset:48
	s_waitcnt vmcnt(2)
	v_mov_b32_e32 v38, v25
	s_waitcnt vmcnt(1)
	v_mov_b32_e32 v36, v29
	v_mov_b32_e32 v37, v30
	v_mov_b32_e32 v39, v26
	v_mov_b32_e32 v29, v31
	v_mov_b32_e32 v25, v27
	v_mov_b32_e32 v26, v21
	v_pk_add_f32 v[28:29], v[36:37], v[28:29]
	v_pk_add_f32 v[24:25], v[38:39], v[24:25]
	v_pk_add_f32 v[20:21], v[20:21], v[26:27]
	v_mov_b32_e32 v26, v23
	v_pk_add_f32 v[28:29], v[28:29], v[28:29] op_sel:[0,1] op_sel_hi:[1,0]
	v_pk_add_f32 v[24:25], v[24:25], v[24:25] op_sel:[0,1] op_sel_hi:[1,0]
	v_pk_add_f32 v[22:23], v[22:23], v[26:27]
	s_waitcnt vmcnt(0)
	v_mov_b32_e32 v29, v32
	v_mov_b32_e32 v25, v33
	v_mov_b32_e32 v21, v34
	v_mov_b32_e32 v23, v35
	v_pk_add_f32 v[24:25], v[28:29], v[24:25]
	v_pk_add_f32 v[20:21], v[20:21], v[22:23]
	s_nop 0
	v_pk_add_f32 v[58:59], v[24:25], v[20:21]
	global_load_dwordx4 v[20:23], v[48:49], off offset:112
	global_load_dwordx4 v[24:27], v[48:49], off offset:48
	global_load_dwordx4 v[28:31], v[48:49], off offset:96
	global_load_dwordx4 v[32:35], v[48:49], off offset:32
	global_load_dwordx4 v[36:39], v[48:49], off offset:80
	global_load_dwordx4 v[40:43], v[48:49], off offset:16
	global_load_dwordx4 v[44:47], v[48:49], off offset:64
	s_nop 0
	global_load_dwordx4 v[48:51], v[48:49], off
	v_mov_b32_e32 v55, v58
	v_mov_b32_e32 v57, v59
	s_waitcnt vmcnt(1)
	v_mov_b32_e32 v61, v44
	s_waitcnt vmcnt(0)
	v_mov_b32_e32 v60, v48
	v_mov_b32_e32 v44, v49
	v_mov_b32_e32 v48, v50
	v_mov_b32_e32 v49, v46
	v_mov_b32_e32 v46, v51
	v_pk_add_f32 v[44:45], v[60:61], v[44:45]
	v_pk_add_f32 v[46:47], v[48:49], v[46:47]
	s_nop 0
	v_pk_add_f32 v[44:45], v[44:45], v[46:47]
	v_mov_b32_e32 v46, v40
	v_mov_b32_e32 v47, v36
	v_mov_b32_e32 v36, v41
	v_mov_b32_e32 v40, v42
	v_mov_b32_e32 v41, v38
	v_mov_b32_e32 v38, v43
	v_pk_add_f32 v[36:37], v[46:47], v[36:37]
	v_pk_add_f32 v[38:39], v[40:41], v[38:39]
	s_nop 0
	v_pk_add_f32 v[36:37], v[36:37], v[38:39]
	v_mov_b32_e32 v38, v32
	v_mov_b32_e32 v39, v28
	v_mov_b32_e32 v28, v33
	v_mov_b32_e32 v32, v34
	v_mov_b32_e32 v33, v30
	v_mov_b32_e32 v30, v35
	v_pk_add_f32 v[28:29], v[38:39], v[28:29]
	v_pk_add_f32 v[30:31], v[32:33], v[30:31]
	v_pk_add_f32 v[36:37], v[44:45], v[36:37]
	v_pk_add_f32 v[28:29], v[28:29], v[30:31]
	v_mov_b32_e32 v30, v24
	v_mov_b32_e32 v31, v20
	v_mov_b32_e32 v20, v25
	v_mov_b32_e32 v24, v26
	v_mov_b32_e32 v25, v22
	v_mov_b32_e32 v22, v27
	v_pk_add_f32 v[20:21], v[30:31], v[20:21]
	v_pk_add_f32 v[22:23], v[24:25], v[22:23]
	v_pk_add_f32 v[28:29], v[36:37], v[28:29]
	v_pk_add_f32 v[20:21], v[20:21], v[22:23]
	s_nop 0
	v_pk_add_f32 v[20:21], v[28:29], v[20:21]
	s_nop 0
	v_pk_fma_f32 v[20:21], v[20:21], s[18:19], v[0:1] op_sel_hi:[1,0,0]
	s_nop 0
	v_mul_f32_e32 v22, 0x4b800000, v20
	v_cmp_gt_f32_e64 s[0:1], s96, v20
	v_cmp_gt_f32_e32 vcc, s96, v21
	s_nop 0
	v_cndmask_b32_e64 v20, v20, v22, s[0:1]
	v_mul_f32_e32 v22, 0x4b800000, v21
	v_cndmask_b32_e32 v21, v21, v22, vcc
	v_rsq_f32_e32 v20, v20
	v_rsq_f32_e32 v21, v21
	s_nop 0
	v_pk_mul_f32 v[22:23], v[20:21], s[20:21] op_sel_hi:[1,0]
	s_nop 0
	v_cndmask_b32_e32 v21, v21, v23, vcc
	v_cndmask_b32_e64 v20, v20, v22, s[0:1]
	v_pk_add_f32 v[22:23], v[54:55], v[56:57]
	v_pk_mul_f32 v[16:17], v[16:17], v[20:21]
	v_pk_fma_f32 v[0:1], v[22:23], s[18:19], v[0:1] op_sel_hi:[1,0,0]
	v_cvt_pk_bf16_f32 v16, v16, v17
	v_mul_f32_e32 v17, 0x4b800000, v0
	v_cmp_gt_f32_e64 s[0:1], s96, v0
	v_cmp_gt_f32_e32 vcc, s96, v1
	v_pk_mul_f32 v[8:9], v[8:9], v[20:21]
	v_cndmask_b32_e64 v0, v0, v17, s[0:1]
	v_mul_f32_e32 v17, 0x4b800000, v1
	v_cndmask_b32_e32 v1, v1, v17, vcc
	v_rsq_f32_e32 v0, v0
	v_rsq_f32_e32 v1, v1
	v_cvt_pk_bf16_f32 v8, v8, v9
	v_pk_mul_f32 v[12:13], v[12:13], v[20:21]
	v_pk_mul_f32 v[4:5], v[4:5], v[20:21]
	v_pk_mul_f32 v[22:23], v[0:1], s[20:21] op_sel_hi:[1,0]
	v_cvt_pk_bf16_f32 v12, v12, v13
	v_cndmask_b32_e32 v1, v1, v23, vcc
	v_cndmask_b32_e64 v0, v0, v22, s[0:1]
	v_pk_mul_f32 v[10:11], v[10:11], v[0:1]
	v_lshlrev_b64 v[22:23], 1, v[52:53]
	v_cvt_pk_bf16_f32 v9, v10, v11
	v_or_b32_e32 v10, 32, v2
	v_mad_i64_i32 v[10:11], s[0:1], v10, s21, v[84:85]
	v_pk_mul_f32 v[14:15], v[14:15], v[0:1]
	v_lshl_add_u64 v[10:11], v[10:11], 0, v[22:23]
	v_pk_mul_f32 v[18:19], v[18:19], v[0:1]
	v_cvt_pk_bf16_f32 v13, v14, v15
	v_or_b32_e32 v14, 16, v2
	global_store_dwordx2 v[10:11], v[8:9], off
	v_cvt_pk_bf16_f32 v8, v4, v5
	v_pk_mul_f32 v[4:5], v[6:7], v[0:1]
	v_or_b32_e32 v0, 48, v2
	v_cvt_pk_bf16_f32 v17, v18, v19
	v_mad_i64_i32 v[18:19], s[0:1], v2, s21, v[84:85]
	v_mad_i64_i32 v[14:15], s[0:1], v14, s21, v[84:85]
	v_mad_i64_i32 v[0:1], s[0:1], v0, s21, v[84:85]
	v_lshl_add_u64 v[18:19], v[18:19], 0, v[22:23]
	v_lshl_add_u64 v[14:15], v[14:15], 0, v[22:23]
	v_lshl_add_u64 v[6:7], v[0:1], 0, v[22:23]
	global_store_dwordx2 v[18:19], v[16:17], off
	global_store_dwordx2 v[14:15], v[12:13], off
	global_store_dword v[6:7], v8, off
	s_branch .LBB0_83

; template <int MODE, bool SWAP, int MT>
; DI void gemm_tile(const int wv_, const Params& p, const u16* __restrict__ A, const u16* __restrict__ Bt, int brow, int bcol, char* smem, const float* gnext) {
;     ...
;   for (int t = 0; t < 32; ++t) {
;     asm volatile("s_waitcnt vmcnt(0)" ::: "memory");
;     __syncthreads();
;     if (t + 1 < 32) stage(t + 1, (t + 1) & 1);
;     const char* sA = smem + (t & 1) * 24576; const char* sB = sA + 16384;
;     bf16x8 Af[MT], Bf[4];
; #pragma unroll
;     for (int n = 0; n < 4; ++n) Bf[n] = *(const bf16x8*)(sB + (wc * 64 + n * 16 + fr) * 64 + fq * 16);
;     constexpr int MH = MT >= 2 ? MT / 2 : 1;
; #pragma unroll
;     for (int m = 0; m < MH; ++m) Af[m] = *(const bf16x8*)(sA + (wr * (16 * MT) + m * 16 + fr) * 64 + fq * 16);
;     __builtin_amdgcn_sched_barrier(0);
; #pragma unroll
;     for (int m = MH; m < MT; ++m) Af[m] = *(const bf16x8*)(sA + (wr * (16 * MT) + m * 16 + fr) * 64 + fq * 16);
; #pragma unroll
;     for (int m = 0; m < MH; ++m)
; #pragma unroll
;       for (int n = 0; n < 4; ++n)
;         acc[m][n] = SWAP ? __builtin_amdgcn_mfma_f32_16x16x32_bf16(Bf[n], Af[m], acc[m][n], 0, 0, 0)
;                          : __builtin_amdgcn_mfma_f32_16x16x32_bf16(Af[m], Bf[n], acc[m][n], 0, 0, 0);
;     __builtin_amdgcn_sched_barrier(0);
; #pragma unroll
;     for (int m = MH; m < MT; ++m)
; #pragma unroll
;       for (int n = 0; n < 4; ++n)
;         acc[m][n] = SWAP ? __builtin_amdgcn_mfma_f32_16x16x32_bf16(Bf[n], Af[m], acc[m][n], 0, 0, 0)
;                          : __builtin_amdgcn_mfma_f32_16x16x32_bf16(Af[m], Bf[n], acc[m][n], 0, 0, 0);
;   }
; template <int MODE>
; DI void phase_gemm(const int wv_, const Params& p, const u16* A, const u16* Bt, int NT, char* smem, const float* gnext) {
;     ...
;   for (int tile = bid_; tile < nfull; tile += nblk_) {
;     int tm = tile / NT, tn = tile - tm * NT;
;     if (MODE == 1 && tn >= 20 && tn < 24) gemm_tile<1, false, 4>(wv_, p, A, Bt, tm * 256, tn * 128, smem, gnext);
;     else gemm_tile<MODE, true, 4>(wv_, p, A, Bt, tm * 256, tn * 128, smem, gnext);
.LBB0_373:
	s_add_i32 s6, s1, 1
	s_bitcmp1_b32 s6, 0
	s_cselect_b32 s7, 0x6000, 0
	v_add_u32_e32 v2, s7, v76
	v_add_u32_e32 v80, 0x2000, v2
	v_readfirstlane_b32 s7, v2
	s_mov_b32 m0, s7
	v_readfirstlane_b32 s7, v80
	v_add_u32_e32 v2, 0x4000, v2
	s_waitcnt vmcnt(0)
	s_waitcnt vmcnt(0) lgkmcnt(0)
	s_barrier
	global_load_lds_dwordx4 v[0:1], off
	s_mov_b32 m0, s7
	v_readfirstlane_b32 s7, v2
	global_load_lds_dwordx4 v[68:69], off
	s_mov_b32 m0, s7
	s_bitcmp1_b32 s1, 0
	global_load_lds_dwordx4 v[70:71], off
	s_cselect_b32 s1, 0x6000, 0
	v_or_b32_e32 v2, s1, v77
	v_add_u32_e32 v92, v2, v78
	ds_read_b128 v[80:83], v92 offset:16384
	ds_read_b128 v[84:87], v92 offset:17408
	ds_read_b128 v[88:91], v92 offset:18432
	ds_read_b128 v[92:95], v92 offset:19456
	v_add_u32_e32 v2, v2, v79
	ds_read_b128 v[96:99], v2
	ds_read_b128 v[100:103], v2 offset:1024
	s_waitcnt lgkmcnt(0)
	v_mfma_f32_16x16x32_bf16 v[64:67], v[80:83], v[96:99], v[64:67]
	v_mfma_f32_16x16x32_bf16 v[60:63], v[84:87], v[96:99], v[60:63]
	v_mfma_f32_16x16x32_bf16 v[56:59], v[88:91], v[96:99], v[56:59]
	v_mfma_f32_16x16x32_bf16 v[52:55], v[92:95], v[96:99], v[52:55]
	ds_read_b128 v[96:99], v2 offset:2048
	ds_read_b128 v[104:107], v2 offset:3072
	v_mfma_f32_16x16x32_bf16 v[48:51], v[80:83], v[100:103], v[48:51]
	v_mfma_f32_16x16x32_bf16 v[40:43], v[84:87], v[100:103], v[40:43]
	v_mfma_f32_16x16x32_bf16 v[36:39], v[88:91], v[100:103], v[36:39]
	v_mfma_f32_16x16x32_bf16 v[44:47], v[92:95], v[100:103], v[44:47]
	s_waitcnt lgkmcnt(0)
	v_mfma_f32_16x16x32_bf16 v[32:35], v[80:83], v[96:99], v[32:35]
	v_lshl_add_u64 v[0:1], v[0:1], 0, 64
	v_lshl_add_u64 v[68:69], v[68:69], 0, 64
	v_lshl_add_u64 v[70:71], v[70:71], 0, 64
	v_mfma_f32_16x16x32_bf16 v[28:31], v[84:87], v[96:99], v[28:31]
	s_cmp_eq_u32 s6, 31
	s_mov_b32 s1, s6
	v_mfma_f32_16x16x32_bf16 v[24:27], v[88:91], v[96:99], v[24:27]
	v_mfma_f32_16x16x32_bf16 v[20:23], v[92:95], v[96:99], v[20:23]
	v_mfma_f32_16x16x32_bf16 v[16:19], v[80:83], v[104:107], v[16:19]
	v_mfma_f32_16x16x32_bf16 v[12:15], v[84:87], v[104:107], v[12:15]
	v_mfma_f32_16x16x32_bf16 v[8:11], v[88:91], v[104:107], v[8:11]
	v_mfma_f32_16x16x32_bf16 v[4:7], v[92:95], v[104:107], v[4:7]
	s_cbranch_scc0 .LBB0_373
	s_add_i32 s98, s22, s13
	s_cmp_lt_i32 s98, s14
	s_cselect_b32 s98, s98, s22
	s_mul_hi_u32 s99, s98, 0x3e0f83e1
	s_lshr_b32 s99, s99, 3
	s_mul_i32 s100, s99, 33
	s_sub_i32 s100, s98, s100
	s_lshl_b32 s99, s99, 8
	s_sub_i32 s98, s99, s0
	s_add_i32 s98, s98, -1
	s_ashr_i32 s99, s98, 31
	s_lshl_b64 s[98:99], s[98:99], 11
	s_lshl_b32 s100, s100, 7
	s_sub_i32 s100, s100, s23
	s_add_i32 s100, s100, -1
	s_ashr_i32 s101, s100, 31
	s_lshl_b64 s[100:101], s[100:101], 11
	v_lshl_add_u64 v[112:113], v[0:1], 0, s[98:99]
	v_lshl_add_u64 v[114:115], v[68:69], 0, s[98:99]
	v_lshl_add_u64 v[116:117], v[70:71], 0, s[100:101]
	v_add_u32_e32 v0, v77, v79
	v_add_u32_e32 v1, v77, v78
	s_waitcnt vmcnt(0)
	s_waitcnt vmcnt(0)
	s_barrier
	global_load_dword v108, v[112:113], off
	global_load_dword v109, v[114:115], off
	global_load_dword v110, v[116:117], off
	ds_read_b128 v[68:71], v0 offset:25600
	ds_read_b128 v[80:83], v0 offset:24576
	ds_read_b128 v[76:79], v1 offset:44032
	ds_read_b128 v[84:87], v1 offset:43008
	ds_read_b128 v[88:91], v1 offset:41984
	ds_read_b128 v[92:95], v1 offset:40960
	s_waitcnt lgkmcnt(0)
	v_mfma_f32_16x16x32_bf16 v[64:67], v[92:95], v[80:83], v[64:67]
	v_mfma_f32_16x16x32_bf16 v[60:63], v[88:91], v[80:83], v[60:63]
	v_mfma_f32_16x16x32_bf16 v[56:59], v[84:87], v[80:83], v[56:59]
	v_mfma_f32_16x16x32_bf16 v[52:55], v[76:79], v[80:83], v[52:55]
	ds_read_b128 v[80:83], v0 offset:26624
	ds_read_b128 v[96:99], v0 offset:27648
	v_mfma_f32_16x16x32_bf16 v[48:51], v[92:95], v[68:71], v[48:51]
	v_mfma_f32_16x16x32_bf16 v[40:43], v[88:91], v[68:71], v[40:43]
	v_mfma_f32_16x16x32_bf16 v[36:39], v[84:87], v[68:71], v[36:39]
	v_mfma_f32_16x16x32_bf16 v[44:47], v[76:79], v[68:71], v[44:47]
	v_or_b32_e32 v0, s0, v75
	v_lshl_add_u32 v68, v74, 6, v0
	v_ashrrev_i32_e32 v69, 31, v68
	v_lshlrev_b64 v[70:71], 6, v[68:69]
	v_lshl_add_u64 v[74:75], s[90:91], 0, v[70:71]
	s_waitcnt lgkmcnt(1)
	v_mfma_f32_16x16x32_bf16 v[32:35], v[92:95], v[80:83], v[32:35]
	s_waitcnt lgkmcnt(0)
	s_barrier
; DI unsigned pack2(float a, float b) { f32x2_t v = {a, b}; return __builtin_bit_cast(unsigned, __builtin_convertvector(v, bf16x2_t)); }
; template <int MODE, bool SWAP, int MT>
; DI void gemm_tile(const int wv_, const Params& p, const u16* __restrict__ A, const u16* __restrict__ Bt, int brow, int bcol, char* smem, const float* gnext) {
;     ...
;         const float rs = rowscale(p.ss, R);
; #pragma unroll
;         for (int n = 0; n < 4; ++n) { acc[m][n][0] *= rs; acc[m][n][1] *= rs; acc[m][n][2] *= rs; acc[m][n][3] *= rs; }
;         if (MODE == 0 && bcol >= 512 && bcol < 1536) {
;           int b = R / P, pos = R - b * P;
;           u16* dstb = (bcol < 1024 ? p.kc : p.vc);
; #pragma unroll
;           for (int n = 0; n < 4; ++n) {
;             int cc = (bcol & 511) + wc * 64 + n * 16 + fq * 4;
;             uint2 o; o.x = pack2(acc[m][n][0], acc[m][n][1]); o.y = pack2(acc[m][n][2], acc[m][n][3]);
;             *(uint2*)(dstb + ((size_t)((b * 8 + (cc >> 6)) * P + pos)) * 64 + (cc & 63)) = o;
;           }
;         } else {
;           const int LD = MODE == 0 ? LD_AB : LD_CD;
;           u16* pr = p.proj + (size_t)R * LD;
; #pragma unroll
;           for (int n = 0; n < 4; ++n) {
;             int col = bcol + wc * 64 + n * 16 + fq * 4;
;             if (MODE == 1 || col < 4184) {
;               uint2 o; o.x = pack2(acc[m][n][0], acc[m][n][1]); o.y = pack2(acc[m][n][2], acc[m][n][3]);
;               int pcol = (MODE == 0 && col >= 1536) ? col - 1024 : col;
;               *(uint2*)(pr + pcol) = o;
;               if (MODE == 0 && col >= 2560 && col < 2624) *(uint2*)(p.ikc + (size_t)R * 64 + (col - 2560)) = o;
	v_mfma_f32_16x16x32_bf16 v[28:31], v[88:91], v[80:83], v[28:31]
	v_lshlrev_b32_e32 v2, 2, v73
	s_add_i32 s0, s23, 0xfffffe00
	s_cmpk_gt_u32 s0, 0x3ff
	v_mfma_f32_16x16x32_bf16 v[24:27], v[84:87], v[80:83], v[24:27]
	s_cselect_b64 s[8:9], -1, 0
	s_cmpk_lt_u32 s23, 0x400
	s_movk_i32 s0, 0x1058
	v_mfma_f32_16x16x32_bf16 v[20:23], v[76:79], v[80:83], v[20:23]
	s_cselect_b64 s[6:7], -1, 0
	s_mov_b64 s[10:11], -1
	v_mfma_f32_16x16x32_bf16 v[12:15], v[88:91], v[96:99], v[12:15]
	v_mfma_f32_16x16x32_bf16 v[8:11], v[84:87], v[96:99], v[8:11]
	v_mfma_f32_16x16x32_bf16 v[4:7], v[76:79], v[96:99], v[4:7]
	v_lshlrev_b32_e32 v77, 6, v72
	global_load_dwordx4 v[70:73], v[74:75], off offset:32
	global_load_dwordx4 v[78:81], v[74:75], off offset:16
	global_load_dwordx4 v[82:85], v[74:75], off
	global_load_dwordx4 v[86:89], v[74:75], off offset:48
	v_or_b32_e32 v76, s23, v77
	v_mfma_f32_16x16x32_bf16 v[16:19], v[92:95], v[96:99], v[16:19]
	v_or_b32_e32 v0, v76, v2
	v_cmp_gt_i32_e64 s[0:1], s0, v0
	s_waitcnt vmcnt(2)
	v_mov_b32_e32 v90, v79
	s_waitcnt vmcnt(1)
	v_mov_b32_e32 v74, v83
	v_mov_b32_e32 v75, v84
	v_mov_b32_e32 v91, v80
	v_mov_b32_e32 v83, v85
	v_mov_b32_e32 v79, v81
	v_mov_b32_e32 v80, v71
	v_pk_add_f32 v[74:75], v[74:75], v[82:83]
	v_pk_add_f32 v[78:79], v[90:91], v[78:79]
	v_pk_add_f32 v[70:71], v[70:71], v[80:81]
	v_mov_b32_e32 v80, v73
	v_pk_add_f32 v[74:75], v[74:75], v[74:75] op_sel:[0,1] op_sel_hi:[1,0]
	v_pk_add_f32 v[78:79], v[78:79], v[78:79] op_sel:[0,1] op_sel_hi:[1,0]
	v_pk_add_f32 v[72:73], v[72:73], v[80:81]
	s_waitcnt vmcnt(0)
	v_mov_b32_e32 v75, v86
	v_mov_b32_e32 v79, v87
	v_mov_b32_e32 v71, v88
	v_mov_b32_e32 v73, v89
	v_pk_add_f32 v[74:75], v[74:75], v[78:79]
	v_pk_add_f32 v[70:71], v[70:71], v[72:73]
	s_nop 0
	v_pk_add_f32 v[70:71], v[74:75], v[70:71]
	s_nop 0
	v_add_f32_e32 v1, v70, v71
	v_mov_b32_e32 v70, 0x358637bd
	v_fmamk_f32 v1, v1, 0x3a800000, v70
	v_cmp_gt_f32_e32 vcc, s96, v1
	v_mul_f32_e32 v70, 0x4b800000, v1
	s_nop 0
	v_cndmask_b32_e32 v1, v1, v70, vcc
	v_rsq_f32_e32 v1, v1
	s_nop 0
	v_mul_f32_e32 v70, 0x45800000, v1
	v_cndmask_b32_e32 v72, v1, v70, vcc
	v_pk_mul_f32 v[70:71], v[64:65], v[72:73] op_sel_hi:[1,0]
	v_pk_mul_f32 v[66:67], v[66:67], v[72:73] op_sel_hi:[1,0]
	v_pk_mul_f32 v[64:65], v[60:61], v[72:73] op_sel_hi:[1,0]
	v_pk_mul_f32 v[62:63], v[62:63], v[72:73] op_sel_hi:[1,0]
	v_pk_mul_f32 v[60:61], v[56:57], v[72:73] op_sel_hi:[1,0]
	v_pk_mul_f32 v[58:59], v[58:59], v[72:73] op_sel_hi:[1,0]
	v_pk_mul_f32 v[56:57], v[52:53], v[72:73] op_sel_hi:[1,0]
	v_pk_mul_f32 v[52:53], v[54:55], v[72:73] op_sel_hi:[1,0]
	s_and_b64 vcc, exec, s[8:9]
	s_cbranch_vccz .LBB0_388
	v_mov_b64_e32 v[54:55], s[68:69]
	v_mad_i64_i32 v[72:73], s[10:11], v68, s35, v[54:55]
	v_lshlrev_b64 v[54:55], 7, v[68:69]
	s_and_saveexec_b64 s[10:11], s[0:1]
	s_cbranch_execz .LBB0_378
	s_movk_i32 s0, 0x5ff
	v_add_u32_e32 v1, 0xfffffc00, v0
	v_cmp_lt_i32_e32 vcc, s0, v0
	s_movk_i32 s0, 0xa00
	v_cvt_pk_bf16_f32 v74, v70, v71
	v_cndmask_b32_e32 v78, v0, v1, vcc
	v_ashrrev_i32_e32 v79, 31, v78
	v_cvt_pk_bf16_f32 v75, v66, v67
	v_lshl_add_u64 v[78:79], v[78:79], 1, v[72:73]
	v_cmp_eq_u32_e32 vcc, s0, v76
	global_store_dwordx2 v[78:79], v[74:75], off
	s_and_b64 exec, exec, vcc
	s_cbranch_execz .LBB0_378
	v_lshl_add_u64 v[78:79], s[78:79], 0, v[54:55]
	v_mov_b32_e32 v1, v3
	v_lshl_add_u64 v[78:79], v[0:1], 1, v[78:79]
	v_add_co_u32_e32 v78, vcc, 0xfffff000, v78
	s_nop 1
	v_addc_co_u32_e32 v79, vcc, -1, v79, vcc
	global_store_dwordx2 v[78:79], v[74:75], off offset:-1024

; template <int MODE, bool SWAP, int MT>
; DI void gemm_tile(const int wv_, const Params& p, const u16* __restrict__ A, const u16* __restrict__ Bt, int brow, int bcol, char* smem, const float* gnext) {
;     ...
;   for (int t = 0; t < 32; ++t) {
;     asm volatile("s_waitcnt vmcnt(0)" ::: "memory");
;     __syncthreads();
;     if (t + 1 < 32) stage(t + 1, (t + 1) & 1);
;     const char* sA = smem + (t & 1) * 24576; const char* sB = sA + 16384;
;     bf16x8 Af[MT], Bf[4];
; #pragma unroll
;     for (int n = 0; n < 4; ++n) Bf[n] = *(const bf16x8*)(sB + (wc * 64 + n * 16 + fr) * 64 + fq * 16);
;     constexpr int MH = MT >= 2 ? MT / 2 : 1;
; #pragma unroll
;     for (int m = 0; m < MH; ++m) Af[m] = *(const bf16x8*)(sA + (wr * (16 * MT) + m * 16 + fr) * 64 + fq * 16);
;     __builtin_amdgcn_sched_barrier(0);
; #pragma unroll
;     for (int m = MH; m < MT; ++m) Af[m] = *(const bf16x8*)(sA + (wr * (16 * MT) + m * 16 + fr) * 64 + fq * 16);
; #pragma unroll
;     for (int m = 0; m < MH; ++m)
; #pragma unroll
;       for (int n = 0; n < 4; ++n)
;         acc[m][n] = SWAP ? __builtin_amdgcn_mfma_f32_16x16x32_bf16(Bf[n], Af[m], acc[m][n], 0, 0, 0)
;                          : __builtin_amdgcn_mfma_f32_16x16x32_bf16(Af[m], Bf[n], acc[m][n], 0, 0, 0);
;     __builtin_amdgcn_sched_barrier(0);
; #pragma unroll
;     for (int m = MH; m < MT; ++m)
; #pragma unroll
;       for (int n = 0; n < 4; ++n)
;         acc[m][n] = SWAP ? __builtin_amdgcn_mfma_f32_16x16x32_bf16(Bf[n], Af[m], acc[m][n], 0, 0, 0)
;                          : __builtin_amdgcn_mfma_f32_16x16x32_bf16(Af[m], Bf[n], acc[m][n], 0, 0, 0);
;   }
;   __syncthreads();
;   if (SWAP) {
; #pragma unroll
;     for (int m = 0; m < MT; ++m) {
;       int R = brow + wr * (16 * MT) + m * 16 + fr;
;       if (MODE == 2) {
;         int b = R / P, pos = R - b * P;
;         const bool valid = pos >= 112;
;         float* hr = valid ? hrow(p, b, pos) : nullptr;
; template <int MODE>
; DI void phase_gemm(const int wv_, const Params& p, const u16* A, const u16* Bt, int NT, char* smem, const float* gnext) {
;     ...
;   for (int tile = bid_; tile < nfull; tile += nblk_) {
;     int tm = tile / NT, tn = tile - tm * NT;
;     if (MODE == 1 && tn >= 20 && tn < 24) gemm_tile<1, false, 4>(wv_, p, A, Bt, tm * 256, tn * 128, smem, gnext);
;     else gemm_tile<MODE, true, 4>(wv_, p, A, Bt, tm * 256, tn * 128, smem, gnext);
.LBB0_829:
	s_add_i32 s2, s1, 1
	s_bitcmp1_b32 s2, 0
	s_cselect_b32 s3, 0x6000, 0
	v_add_u32_e32 v2, s3, v74
	v_add_u32_e32 v80, 0x2000, v2
	v_readfirstlane_b32 s3, v2
	s_mov_b32 m0, s3
	v_readfirstlane_b32 s3, v80
	v_add_u32_e32 v2, 0x4000, v2
	s_waitcnt vmcnt(0)
	s_waitcnt vmcnt(0) lgkmcnt(0)
	s_barrier
	global_load_lds_dwordx4 v[0:1], off
	s_mov_b32 m0, s3
	v_readfirstlane_b32 s3, v2
	global_load_lds_dwordx4 v[68:69], off
	s_mov_b32 m0, s3
	s_bitcmp1_b32 s1, 0
	global_load_lds_dwordx4 v[70:71], off
	s_cselect_b32 s1, 0x6000, 0
	v_or_b32_e32 v2, s1, v75
	v_add_u32_e32 v92, v2, v78
	ds_read_b128 v[80:83], v92 offset:16384
	ds_read_b128 v[84:87], v92 offset:17408
	ds_read_b128 v[88:91], v92 offset:18432
	ds_read_b128 v[92:95], v92 offset:19456
	v_add_u32_e32 v2, v2, v79
	ds_read_b128 v[96:99], v2
	ds_read_b128 v[100:103], v2 offset:1024
	s_waitcnt lgkmcnt(0)
	v_mfma_f32_16x16x32_bf16 v[64:67], v[80:83], v[96:99], v[64:67]
	v_mfma_f32_16x16x32_bf16 v[60:63], v[84:87], v[96:99], v[60:63]
	v_mfma_f32_16x16x32_bf16 v[56:59], v[88:91], v[96:99], v[56:59]
	v_mfma_f32_16x16x32_bf16 v[52:55], v[92:95], v[96:99], v[52:55]
	ds_read_b128 v[96:99], v2 offset:2048
	ds_read_b128 v[104:107], v2 offset:3072
	v_mfma_f32_16x16x32_bf16 v[48:51], v[80:83], v[100:103], v[48:51]
	v_mfma_f32_16x16x32_bf16 v[44:47], v[84:87], v[100:103], v[44:47]
	v_mfma_f32_16x16x32_bf16 v[40:43], v[88:91], v[100:103], v[40:43]
	v_mfma_f32_16x16x32_bf16 v[36:39], v[92:95], v[100:103], v[36:39]
	s_waitcnt lgkmcnt(0)
	v_mfma_f32_16x16x32_bf16 v[32:35], v[80:83], v[96:99], v[32:35]
	v_lshl_add_u64 v[0:1], v[0:1], 0, 64
	v_lshl_add_u64 v[68:69], v[68:69], 0, 64
	v_lshl_add_u64 v[70:71], v[70:71], 0, 64
	v_mfma_f32_16x16x32_bf16 v[28:31], v[84:87], v[96:99], v[28:31]
	s_cmp_eq_u32 s2, 31
	s_mov_b32 s1, s2
	v_mfma_f32_16x16x32_bf16 v[24:27], v[88:91], v[96:99], v[24:27]
	v_mfma_f32_16x16x32_bf16 v[20:23], v[92:95], v[96:99], v[20:23]
	v_mfma_f32_16x16x32_bf16 v[16:19], v[80:83], v[104:107], v[16:19]
	v_mfma_f32_16x16x32_bf16 v[12:15], v[84:87], v[104:107], v[12:15]
	v_mfma_f32_16x16x32_bf16 v[8:11], v[88:91], v[104:107], v[8:11]
	v_mfma_f32_16x16x32_bf16 v[4:7], v[92:95], v[104:107], v[4:7]
	s_cbranch_scc0 .LBB0_829
	s_add_i32 s98, s28, s20
	s_cmp_lt_i32 s98, s21
	s_cselect_b32 s98, s98, s28
	s_lshr_b32 s99, s98, 3
	s_and_b32 s100, s98, 7
	s_lshl_b32 s99, s99, 8
	s_sub_i32 s98, s99, s0
	s_add_i32 s98, s98, -1
	s_ashr_i32 s99, s98, 31
	s_lshl_b64 s[98:99], s[98:99], 11
	s_lshl_b32 s100, s100, 7
	s_sub_i32 s100, s100, s12
	s_add_i32 s100, s100, -1
	s_ashr_i32 s101, s100, 31
	s_lshl_b64 s[100:101], s[100:101], 11
	v_lshl_add_u64 v[112:113], v[0:1], 0, s[98:99]
	v_lshl_add_u64 v[114:115], v[68:69], 0, s[98:99]
	v_lshl_add_u64 v[116:117], v[70:71], 0, s[100:101]
	v_add_u32_e32 v0, v75, v79
	v_add_u32_e32 v1, v75, v78
	s_waitcnt vmcnt(0)
	s_waitcnt vmcnt(0)
	s_barrier
	global_load_dword v108, v[112:113], off
	global_load_dword v109, v[114:115], off
	global_load_dword v110, v[116:117], off
	ds_read_b128 v[80:83], v0 offset:25600
	ds_read_b128 v[84:87], v0 offset:24576
	ds_read_b128 v[88:91], v1 offset:44032
	ds_read_b128 v[92:95], v1 offset:43008
	ds_read_b128 v[96:99], v1 offset:41984
	ds_read_b128 v[100:103], v1 offset:40960
	s_waitcnt lgkmcnt(0)
	v_mfma_f32_16x16x32_bf16 v[68:71], v[100:103], v[84:87], v[64:67]
	v_mfma_f32_16x16x32_bf16 v[60:63], v[96:99], v[84:87], v[60:63]
	v_mfma_f32_16x16x32_bf16 v[56:59], v[92:95], v[84:87], v[56:59]
	v_mfma_f32_16x16x32_bf16 v[52:55], v[88:91], v[84:87], v[52:55]
	ds_read_b128 v[64:67], v0 offset:26624
	ds_read_b128 v[84:87], v0 offset:27648
	v_mfma_f32_16x16x32_bf16 v[48:51], v[100:103], v[80:83], v[48:51]
	v_mfma_f32_16x16x32_bf16 v[44:47], v[96:99], v[80:83], v[44:47]
	v_mfma_f32_16x16x32_bf16 v[40:43], v[92:95], v[80:83], v[40:43]
	v_mfma_f32_16x16x32_bf16 v[36:39], v[88:91], v[80:83], v[36:39]
	v_or_b32_e32 v0, s0, v73
	v_lshl_add_u32 v72, v72, 6, v0
	s_mov_b32 s0, 0x7e07e07f
	v_mul_hi_i32 v0, v72, s0
	s_waitcnt lgkmcnt(1)
	v_mfma_f32_16x16x32_bf16 v[32:35], v[100:103], v[64:67], v[32:35]
	v_lshrrev_b32_e32 v1, 31, v0
	v_ashrrev_i32_e32 v0, 12, v0
	v_add_u32_e32 v0, v0, v1
	v_mfma_f32_16x16x32_bf16 v[28:31], v[96:99], v[64:67], v[28:31]
	s_movk_i32 s0, 0xdf80
	v_mad_i32_i24 v1, v0, s0, v72
	v_cmp_lt_i32_e64 s[2:3], s54, v1
	v_mfma_f32_16x16x32_bf16 v[24:27], v[92:95], v[64:67], v[24:27]
	v_mov_b64_e32 v[74:75], 0
	s_waitcnt lgkmcnt(0)
	s_barrier
	v_mfma_f32_16x16x32_bf16 v[20:23], v[88:91], v[64:67], v[20:23]
	v_mfma_f32_16x16x32_bf16 v[16:19], v[100:103], v[84:87], v[16:19]
	v_mfma_f32_16x16x32_bf16 v[12:15], v[96:99], v[84:87], v[12:15]
	v_mfma_f32_16x16x32_bf16 v[8:11], v[92:95], v[84:87], v[8:11]
	v_mfma_f32_16x16x32_bf16 v[4:7], v[88:91], v[84:87], v[4:7]
	s_and_saveexec_b64 s[0:1], s[2:3]
	s_cbranch_execz .LBB0_832
	s_movk_i32 s4, 0x7f
	v_cmp_lt_u32_e32 vcc, s4, v1
	v_mov_b32_e32 v64, 0xffffff90
	v_mov_b32_e32 v65, 0xffffff80
	v_cndmask_b32_e64 v2, 4, 13, vcc
	v_cndmask_b32_e32 v66, v64, v65, vcc
	v_lshlrev_b32_e32 v0, v2, v0
	v_mov_b32_e32 v64, s85
	v_mov_b32_e32 v65, s43
	v_add3_u32 v0, v66, v1, v0
	v_cndmask_b32_e32 v65, v64, v65, vcc
	v_mov_b32_e32 v64, s84
	v_mov_b32_e32 v67, s42
	v_ashrrev_i32_e32 v1, 31, v0
	v_cndmask_b32_e32 v64, v64, v67, vcc
	v_lshlrev_b64 v[0:1], 12, v[0:1]
	v_lshl_add_u64 v[74:75], v[64:65], 0, v[0:1]
